# attention window bias: 32 masked LDS-read branches -> ds_read2+cndmask; conv: SGA loads hoisted; G2 epilogue loads hoisted
# speedup vs baseline: 1.0143x; 1.0129x over previous
.LBB0_478:
	s_or_saveexec_b64 s[72:73], s[72:73]
	v_mov_b64_e32 v[40:41], s[90:91]
	s_xor_b64 exec, exec, s[72:73]
	v_ashrrev_i32_e32 v39, 31, v38
	v_lshlrev_b64 v[34:35], 7, v[38:39]
	v_lshl_add_u64 v[34:35], v[156:157], 0, v[34:35]
	v_ashrrev_i32_e32 v37, 31, v36
	v_mov_b64_e32 v[40:41], v[158:159]
	s_or_b64 exec, exec, s[72:73]
	v_mov_b32_e32 v141, v133
	v_lshlrev_b64 v[36:37], 13, v[36:37]
	v_lshl_add_u64 v[38:39], v[34:35], 0, v[132:133]
	v_mov_b32_e32 v137, v133
	v_lshl_add_u64 v[34:35], v[34:35], 0, v[140:141]
	v_lshl_add_u64 v[36:37], v[40:41], 0, v[36:37]
	v_lshl_add_u64 v[38:39], v[38:39], 0, v[136:137]
	v_lshl_add_u64 v[34:35], v[34:35], 0, v[136:137]
	global_load_dwordx4 v[126:129], v[38:39], off
	global_load_dwordx4 v[122:125], v[34:35], off
	v_lshl_add_u64 v[34:35], v[36:37], 0, v[132:133]
	v_lshl_add_u64 v[34:35], v[34:35], 0, v[136:137]
	v_lshl_add_u64 v[36:37], v[36:37], 0, v[140:141]
	v_lshl_add_u64 v[36:37], v[36:37], 0, v[136:137]
	global_load_dwordx4 v[118:121], v[34:35], off
	global_load_dwordx4 v[114:117], v[36:37], off
	s_cmp_gt_u32 s3, 7
	s_cselect_b64 s[72:73], -1, 0
	s_and_b64 s[94:95], s[0:1], s[72:73]
	v_mov_b32_e32 v66, 0
	s_mov_b64 vcc, -1
	s_and_saveexec_b64 s[76:77], s[94:95]
	v_add_u32_e32 v34, s3, v189
	v_cmp_ge_i32_e32 vcc, v34, v182
	v_cmp_lt_i32_e64 s[72:73], v34, v186
	s_and_b64 s[72:73], vcc, s[72:73]
	s_orn2_b64 vcc, s[72:73], exec
	v_mov_b32_e32 v66, v188
	s_or_b64 exec, exec, s[76:77]
	s_and_saveexec_b64 s[72:73], vcc
	s_cbranch_execz .LBB0_475
	s_bitcmp1_b32 s3, 0
	s_cselect_b32 s3, 0x4800, 0
	v_add_u32_e32 v137, s3, v173
	ds_read_b128 v[34:37], v137
	ds_read_b128 v[68:71], v137 offset:32
	s_waitcnt lgkmcnt(1)
	v_mfma_f32_32x32x16_bf16 v[50:65], v[34:37], v[98:101], 0
	ds_read_b128 v[34:37], v137 offset:4608
	s_waitcnt lgkmcnt(1)
	v_mfma_f32_32x32x16_bf16 v[50:65], v[68:71], v[102:105], v[50:65]
	ds_read_b128 v[68:71], v137 offset:4640
	s_waitcnt lgkmcnt(1)
	v_mfma_f32_32x32x16_bf16 v[34:49], v[34:37], v[98:101], 0
	s_waitcnt lgkmcnt(0)
	v_mfma_f32_32x32x16_bf16 v[34:49], v[68:71], v[102:105], v[34:49]
	ds_read_b128 v[68:71], v137 offset:64
	s_waitcnt lgkmcnt(0)
	v_mfma_f32_32x32x16_bf16 v[50:65], v[68:71], v[106:109], v[50:65]
	ds_read_b128 v[68:71], v137 offset:4672
	s_waitcnt lgkmcnt(0)
	v_mfma_f32_32x32x16_bf16 v[34:49], v[68:71], v[106:109], v[34:49]
	ds_read_b128 v[68:71], v137 offset:96
	s_waitcnt lgkmcnt(0)
	v_mfma_f32_32x32x16_bf16 v[50:65], v[68:71], v[110:113], v[50:65]
	ds_read_b128 v[68:71], v137 offset:4704
	s_waitcnt lgkmcnt(0)
	v_mfma_f32_32x32x16_bf16 v[34:49], v[68:71], v[110:113], v[34:49]
	s_and_saveexec_b64 vcc, s[94:95]
	s_cbranch_execz .LBB0_549
	v_lshl_add_u32 v141, v66, 2, v187
	v_add_u32_e32 v141, 0x903c, v141
	v_mov_b32_e32 v246, 0xff800000
	ds_read2_b32 v[82:83], v141 offset0:0 offset1:1
	ds_read2_b32 v[84:85], v141 offset0:2 offset1:3
	ds_read2_b32 v[86:87], v141 offset0:8 offset1:9
	ds_read2_b32 v[88:89], v141 offset0:10 offset1:11
	ds_read2_b32 v[90:91], v141 offset0:16 offset1:17
	ds_read2_b32 v[92:93], v141 offset0:18 offset1:19
	ds_read2_b32 v[94:95], v141 offset0:24 offset1:25
	ds_read2_b32 v[96:97], v141 offset0:26 offset1:27
	ds_read2_b32 v[66:67], v141 offset0:32 offset1:33
	ds_read2_b32 v[68:69], v141 offset0:34 offset1:35
	ds_read2_b32 v[70:71], v141 offset0:40 offset1:41
	ds_read2_b32 v[72:73], v141 offset0:42 offset1:43
	ds_read2_b32 v[74:75], v141 offset0:48 offset1:49
	ds_read2_b32 v[76:77], v141 offset0:50 offset1:51
	ds_read2_b32 v[78:79], v141 offset0:56 offset1:57
	ds_read2_b32 v[80:81], v141 offset0:58 offset1:59
	s_waitcnt lgkmcnt(8)
	v_pk_add_f32 v[82:83], v[50:51], v[82:83]
	v_pk_add_f32 v[84:85], v[52:53], v[84:85]
	v_pk_add_f32 v[86:87], v[54:55], v[86:87]
	v_pk_add_f32 v[88:89], v[56:57], v[88:89]
	v_pk_add_f32 v[90:91], v[58:59], v[90:91]
	v_pk_add_f32 v[92:93], v[60:61], v[92:93]
	v_pk_add_f32 v[94:95], v[62:63], v[94:95]
	v_pk_add_f32 v[96:97], v[64:65], v[96:97]
	v_cndmask_b32_e64 v50, v246, v82, s[4:5]
	v_cndmask_b32_e64 v51, v246, v83, s[8:9]
	v_cndmask_b32_e64 v52, v246, v84, s[12:13]
	v_cndmask_b32_e64 v53, v246, v85, s[16:17]
	v_cndmask_b32_e64 v54, v246, v86, s[20:21]
	v_cndmask_b32_e64 v55, v246, v87, s[24:25]
	v_cndmask_b32_e64 v56, v246, v88, s[28:29]
	v_cndmask_b32_e64 v57, v246, v89, s[34:35]
	v_cndmask_b32_e64 v58, v246, v90, s[38:39]
	v_cndmask_b32_e64 v59, v246, v91, s[42:43]
	v_cndmask_b32_e64 v60, v246, v92, s[46:47]
	v_cndmask_b32_e64 v61, v246, v93, s[50:51]
	v_cndmask_b32_e64 v62, v246, v94, s[54:55]
	v_cndmask_b32_e64 v63, v246, v95, s[58:59]
	v_cndmask_b32_e64 v64, v246, v96, s[62:63]
	v_cndmask_b32_e64 v65, v246, v97, s[66:67]
	s_waitcnt lgkmcnt(0)
	v_pk_add_f32 v[66:67], v[34:35], v[66:67]
	v_pk_add_f32 v[68:69], v[36:37], v[68:69]
	v_pk_add_f32 v[70:71], v[38:39], v[70:71]
	v_pk_add_f32 v[72:73], v[40:41], v[72:73]
	v_pk_add_f32 v[74:75], v[42:43], v[74:75]
	v_pk_add_f32 v[76:77], v[44:45], v[76:77]
	v_pk_add_f32 v[78:79], v[46:47], v[78:79]
	v_pk_add_f32 v[80:81], v[48:49], v[80:81]
	v_cndmask_b32_e64 v34, v246, v66, s[6:7]
	v_cndmask_b32_e64 v35, v246, v67, s[10:11]
	v_cndmask_b32_e64 v36, v246, v68, s[14:15]
	v_cndmask_b32_e64 v37, v246, v69, s[18:19]
	v_cndmask_b32_e64 v38, v246, v70, s[22:23]
	v_cndmask_b32_e64 v39, v246, v71, s[26:27]
	v_cndmask_b32_e64 v40, v246, v72, s[30:31]
	v_cndmask_b32_e64 v41, v246, v73, s[36:37]
	v_cndmask_b32_e64 v42, v246, v74, s[40:41]
	v_cndmask_b32_e64 v43, v246, v75, s[44:45]
	v_cndmask_b32_e64 v44, v246, v76, s[48:49]
	v_cndmask_b32_e64 v45, v246, v77, s[52:53]
	v_cndmask_b32_e64 v46, v246, v78, s[56:57]
	v_cndmask_b32_e64 v47, v246, v79, s[60:61]
	v_cndmask_b32_e64 v48, v246, v80, s[64:65]
	v_cndmask_b32_e64 v49, v246, v81, s[68:69]

.LBB0_555:
	v_lshrrev_b32_e32 v3, 12, v226
	v_cmp_gt_i32_e32 vcc, s10, v1
	v_lshrrev_b32_e32 v2, 4, v1
	v_add_u32_e32 v3, 32, v3
	v_cndmask_b32_e32 v2, v3, v2, vcc
	v_lshlrev_b32_e32 v2, 5, v2
	v_add3_u32 v2, v226, v2, s11
	v_ashrrev_i32_e32 v3, 31, v2
	v_lshlrev_b64 v[136:137], 10, v[2:3]
	v_lshl_add_u64 v[148:149], v[78:79], 0, v[136:137]
	v_add_co_u32_e32 v138, vcc, s7, v148
	s_waitcnt lgkmcnt(0)
	s_nop 0
	v_addc_co_u32_e32 v139, vcc, 0, v149, vcc
	v_add_co_u32_e32 v140, vcc, s12, v148
	s_barrier
	s_nop 0
	v_addc_co_u32_e32 v141, vcc, 0, v149, vcc
	global_load_dwordx2 v[134:135], v[18:19], off
	global_load_dwordx2 v[132:133], v[18:19], off offset:2048
	global_load_dwordx2 v[130:131], v[20:21], off
	global_load_dwordx2 v[128:129], v[22:23], off
	global_load_dwordx2 v[2:3], v[24:25], off
	global_load_dwordx2 v[4:5], v[26:27], off
	global_load_dwordx2 v[6:7], v[28:29], off
	global_load_dwordx2 v[8:9], v[30:31], off
	global_load_dwordx2 v[10:11], v[32:33], off
	global_load_dwordx2 v[12:13], v[34:35], off
	global_load_dwordx2 v[14:15], v[36:37], off
	global_load_dwordx2 v[16:17], v[38:39], off
	global_load_dwordx2 v[90:91], v[40:41], off
	global_load_dwordx2 v[92:93], v[42:43], off
	global_load_dwordx2 v[94:95], v[44:45], off
	global_load_dwordx2 v[96:97], v[46:47], off
	global_load_dwordx2 v[98:99], v[48:49], off
	global_load_dwordx2 v[100:101], v[50:51], off
	global_load_dwordx2 v[102:103], v[52:53], off
	global_load_dwordx2 v[104:105], v[54:55], off
	global_load_dwordx2 v[106:107], v[56:57], off
	global_load_dwordx2 v[108:109], v[58:59], off
	global_load_dwordx2 v[110:111], v[60:61], off
	global_load_dwordx2 v[112:113], v[62:63], off
	global_load_dwordx2 v[114:115], v[64:65], off
	global_load_dwordx2 v[116:117], v[66:67], off
	global_load_dwordx2 v[118:119], v[68:69], off
	global_load_dwordx2 v[120:121], v[70:71], off
	global_load_dwordx2 v[122:123], v[72:73], off
	global_load_dwordx2 v[124:125], v[74:75], off
	global_load_dwordx2 v[126:127], v[76:77], off
	global_load_dwordx2 v[136:137], v[80:81], off
	global_load_dword v145, v[148:149], off offset:1024
	global_load_dword v150, v[148:149], off offset:2048
	global_load_dword v152, v[148:149], off offset:3072
	global_load_dword v156, v[140:141], off offset:-4096
	global_load_dword v158, v[138:139], off offset:1024
	global_load_dword v160, v[138:139], off offset:2048
	global_load_dword v164, v[138:139], off offset:3072
	global_load_dword v166, v[140:141], off
	global_load_dword v168, v[140:141], off offset:1024
	global_load_dword v172, v[140:141], off offset:2048
	global_load_dword v174, v[140:141], off offset:3072
	v_add_co_u32_e32 v138, vcc, s13, v148
	v_add_u32_e32 v1, s8, v1
	s_nop 0
	v_addc_co_u32_e32 v139, vcc, 0, v149, vcc
	v_add_co_u32_e32 v146, vcc, s14, v148
	s_waitcnt vmcnt(7)
	v_lshlrev_b32_e32 v178, 16, v156
	v_addc_co_u32_e32 v147, vcc, 0, v149, vcc
	v_add_co_u32_e32 v154, vcc, s15, v148
	global_load_dword v176, v[146:147], off offset:-4096
	global_load_dword v144, v[138:139], off offset:1024
	global_load_dword v143, v[138:139], off offset:2048
	global_load_dword v142, v[138:139], off offset:3072
	global_load_dword v141, v[146:147], off
	global_load_dword v140, v[146:147], off offset:1024
	s_nop 0
	global_load_dword v138, v[146:147], off offset:2048
	global_load_dword v139, v[146:147], off offset:3072
	v_addc_co_u32_e32 v155, vcc, 0, v149, vcc
	v_add_co_u32_e32 v162, vcc, s16, v148
	v_lshlrev_b32_e32 v170, 16, v152
	s_nop 0
	v_addc_co_u32_e32 v163, vcc, 0, v149, vcc
	global_load_dword v147, v[162:163], off offset:-4096
	global_load_dword v151, v[154:155], off offset:1024
	global_load_dword v153, v[154:155], off offset:2048
	global_load_dword v157, v[154:155], off offset:3072
	global_load_dword v159, v[162:163], off
	global_load_dword v161, v[162:163], off offset:1024
	global_load_dword v165, v[162:163], off offset:2048
	global_load_dword v167, v[162:163], off offset:3072
	v_add_co_u32_e32 v154, vcc, s17, v148
	v_and_b32_e32 v171, 0xffff0000, v152
	s_nop 0
	v_addc_co_u32_e32 v155, vcc, 0, v149, vcc
	v_add_co_u32_e32 v162, vcc, s18, v148
	v_and_b32_e32 v179, 0xffff0000, v156
	s_nop 0
	v_addc_co_u32_e32 v163, vcc, 0, v149, vcc
	global_load_dword v169, v[162:163], off offset:-4096
	global_load_dword v173, v[154:155], off offset:1024
	global_load_dword v175, v[154:155], off offset:2048
	global_load_dword v177, v[154:155], off offset:3072
	global_load_dword v181, v[162:163], off
	global_load_dword v183, v[162:163], off offset:1024
	global_load_dword v185, v[162:163], off offset:2048
	global_load_dword v189, v[162:163], off offset:3072
	v_add_co_u32_e32 v154, vcc, s19, v148
	s_waitcnt vmcnt(30)
	v_lshlrev_b32_e32 v186, 16, v158
	v_addc_co_u32_e32 v155, vcc, 0, v149, vcc
	v_add_co_u32_e32 v162, vcc, s20, v148
	v_and_b32_e32 v187, 0xffff0000, v158
	s_nop 0
	v_addc_co_u32_e32 v163, vcc, 0, v149, vcc
	global_load_dword v191, v[162:163], off offset:-4096
	global_load_dword v193, v[154:155], off offset:1024
	global_load_dword v195, v[154:155], off offset:2048
	global_load_dword v201, v[154:155], off offset:3072
	global_load_dword v203, v[162:163], off
	global_load_dword v205, v[162:163], off offset:1024
	global_load_dword v207, v[162:163], off offset:2048
	global_load_dword v209, v[162:163], off offset:3072
	v_add_co_u32_e32 v154, vcc, s21, v148
	v_lshlrev_b32_e32 v162, 16, v150
	s_nop 0
	v_addc_co_u32_e32 v155, vcc, 0, v149, vcc
	global_load_dword v211, v[154:155], off
	global_load_dword v227, v[154:155], off offset:1024
	global_load_dword v146, v[148:149], off
	v_lshlrev_b32_e32 v154, 16, v145
	v_and_b32_e32 v155, 0xffff0000, v145
	v_and_b32_e32 v163, 0xffff0000, v150
	s_waitcnt vmcnt(40)
	v_lshlrev_b32_e32 v196, 16, v160
	v_and_b32_e32 v197, 0xffff0000, v160
	s_waitcnt vmcnt(39)
	v_lshlrev_b32_e32 v198, 16, v164
	v_and_b32_e32 v199, 0xffff0000, v164
	s_waitcnt vmcnt(25)
	v_lshlrev_b32_e32 v150, 16, v151
	v_and_b32_e32 v151, 0xffff0000, v151
	s_waitcnt vmcnt(24)
	v_lshlrev_b32_e32 v152, 16, v153
	v_and_b32_e32 v153, 0xffff0000, v153
	s_waitcnt vmcnt(23)
	v_lshlrev_b32_e32 v156, 16, v157
	v_and_b32_e32 v157, 0xffff0000, v157
	s_waitcnt vmcnt(22)
	v_lshlrev_b32_e32 v158, 16, v159
	v_and_b32_e32 v159, 0xffff0000, v159
	s_waitcnt vmcnt(21)
	v_lshlrev_b32_e32 v160, 16, v161
	v_and_b32_e32 v161, 0xffff0000, v161
	s_waitcnt vmcnt(20)
	v_lshlrev_b32_e32 v164, 16, v165
	v_and_b32_e32 v165, 0xffff0000, v165
	s_waitcnt vmcnt(14)
	v_lshlrev_b32_e32 v180, 16, v181
	v_and_b32_e32 v181, 0xffff0000, v181
	s_waitcnt vmcnt(13)
	v_lshlrev_b32_e32 v182, 16, v183
	v_and_b32_e32 v183, 0xffff0000, v183
	s_waitcnt vmcnt(12)
	v_lshlrev_b32_e32 v184, 16, v185
	v_and_b32_e32 v185, 0xffff0000, v185
	s_waitcnt vmcnt(11)
	v_lshlrev_b32_e32 v188, 16, v189
	v_and_b32_e32 v189, 0xffff0000, v189
	s_waitcnt vmcnt(10)
	v_lshlrev_b32_e32 v190, 16, v191
	v_and_b32_e32 v191, 0xffff0000, v191
	s_waitcnt vmcnt(9)
	v_lshlrev_b32_e32 v192, 16, v193
	v_and_b32_e32 v193, 0xffff0000, v193
	s_waitcnt vmcnt(8)
	v_lshlrev_b32_e32 v194, 16, v195
	v_and_b32_e32 v195, 0xffff0000, v195
	s_waitcnt vmcnt(7)
	v_lshlrev_b32_e32 v200, 16, v201
	v_and_b32_e32 v201, 0xffff0000, v201
	s_waitcnt vmcnt(6)
	v_lshlrev_b32_e32 v202, 16, v203
	v_and_b32_e32 v203, 0xffff0000, v203
	s_waitcnt vmcnt(5)
	v_lshlrev_b32_e32 v204, 16, v205
	v_and_b32_e32 v205, 0xffff0000, v205
	s_waitcnt vmcnt(0)
	v_lshlrev_b32_e32 v148, 16, v146
	v_and_b32_e32 v149, 0xffff0000, v146
	v_pk_fma_f32 v[148:149], v[148:149], v[134:135], v[136:137]
	v_lshlrev_b32_e32 v146, 16, v147
	v_pk_fma_f32 v[148:149], v[154:155], v[132:133], v[148:149]
	v_pk_fma_f32 v[154:155], v[154:155], v[134:135], v[136:137]
	v_pk_fma_f32 v[148:149], v[162:163], v[130:131], v[148:149]
	v_pk_fma_f32 v[154:155], v[162:163], v[132:133], v[154:155]
	v_pk_fma_f32 v[162:163], v[162:163], v[134:135], v[136:137]
	v_pk_fma_f32 v[148:149], v[170:171], v[128:129], v[148:149]
	v_pk_fma_f32 v[154:155], v[170:171], v[130:131], v[154:155]
	v_pk_fma_f32 v[162:163], v[170:171], v[132:133], v[162:163]
	v_pk_fma_f32 v[170:171], v[170:171], v[134:135], v[136:137]
	v_pk_fma_f32 v[148:149], v[178:179], v[2:3], v[148:149]
	v_pk_fma_f32 v[154:155], v[178:179], v[128:129], v[154:155]
	v_pk_fma_f32 v[162:163], v[178:179], v[130:131], v[162:163]
	v_pk_fma_f32 v[170:171], v[178:179], v[132:133], v[170:171]
	v_pk_fma_f32 v[178:179], v[178:179], v[134:135], v[136:137]
	v_pk_fma_f32 v[148:149], v[186:187], v[4:5], v[148:149]
	v_pk_fma_f32 v[154:155], v[186:187], v[2:3], v[154:155]
	v_pk_fma_f32 v[162:163], v[186:187], v[128:129], v[162:163]
	v_pk_fma_f32 v[170:171], v[186:187], v[130:131], v[170:171]
	v_pk_fma_f32 v[178:179], v[186:187], v[132:133], v[178:179]
	v_pk_fma_f32 v[186:187], v[186:187], v[134:135], v[136:137]
	v_pk_fma_f32 v[148:149], v[196:197], v[6:7], v[148:149]
	v_pk_fma_f32 v[154:155], v[196:197], v[4:5], v[154:155]
	v_pk_fma_f32 v[162:163], v[196:197], v[2:3], v[162:163]
	v_pk_fma_f32 v[170:171], v[196:197], v[128:129], v[170:171]
	v_pk_fma_f32 v[178:179], v[196:197], v[130:131], v[178:179]
	v_pk_fma_f32 v[186:187], v[196:197], v[132:133], v[186:187]
	v_pk_fma_f32 v[196:197], v[196:197], v[134:135], v[136:137]
	v_pk_fma_f32 v[148:149], v[198:199], v[8:9], v[148:149]
	v_pk_fma_f32 v[154:155], v[198:199], v[6:7], v[154:155]
	v_pk_fma_f32 v[162:163], v[198:199], v[4:5], v[162:163]
	v_pk_fma_f32 v[170:171], v[198:199], v[2:3], v[170:171]
	v_pk_fma_f32 v[178:179], v[198:199], v[128:129], v[178:179]
	v_pk_fma_f32 v[186:187], v[198:199], v[130:131], v[186:187]
	v_pk_fma_f32 v[228:229], v[198:199], v[132:133], v[196:197]
	v_pk_fma_f32 v[198:199], v[198:199], v[134:135], v[136:137]
	v_lshlrev_b32_e32 v196, 16, v166
	v_and_b32_e32 v197, 0xffff0000, v166
	v_pk_fma_f32 v[148:149], v[196:197], v[10:11], v[148:149]
	v_pk_fma_f32 v[154:155], v[196:197], v[8:9], v[154:155]
	v_pk_fma_f32 v[162:163], v[196:197], v[6:7], v[162:163]
	v_pk_fma_f32 v[170:171], v[196:197], v[4:5], v[170:171]
	v_pk_fma_f32 v[178:179], v[196:197], v[2:3], v[178:179]
	v_pk_fma_f32 v[186:187], v[196:197], v[128:129], v[186:187]
	v_pk_fma_f32 v[230:231], v[196:197], v[132:133], v[198:199]
	v_lshlrev_b32_e32 v198, 16, v168
	v_and_b32_e32 v199, 0xffff0000, v168
	v_pk_fma_f32 v[228:229], v[196:197], v[130:131], v[228:229]
	v_pk_fma_f32 v[148:149], v[198:199], v[12:13], v[148:149]
	v_pk_fma_f32 v[154:155], v[198:199], v[10:11], v[154:155]
	v_pk_fma_f32 v[162:163], v[198:199], v[8:9], v[162:163]
	v_pk_fma_f32 v[170:171], v[198:199], v[6:7], v[170:171]
	v_pk_fma_f32 v[178:179], v[198:199], v[4:5], v[178:179]
	v_pk_fma_f32 v[232:233], v[198:199], v[2:3], v[186:187]
	v_lshlrev_b32_e32 v186, 16, v172
	v_and_b32_e32 v187, 0xffff0000, v172
	v_pk_fma_f32 v[196:197], v[196:197], v[134:135], v[136:137]
	v_pk_fma_f32 v[228:229], v[198:199], v[128:129], v[228:229]
	v_pk_fma_f32 v[230:231], v[198:199], v[130:131], v[230:231]
	v_pk_fma_f32 v[148:149], v[186:187], v[14:15], v[148:149]
	v_pk_fma_f32 v[154:155], v[186:187], v[12:13], v[154:155]
	v_pk_fma_f32 v[162:163], v[186:187], v[10:11], v[162:163]
	v_pk_fma_f32 v[170:171], v[186:187], v[8:9], v[170:171]
	v_pk_fma_f32 v[234:235], v[186:187], v[6:7], v[178:179]
	v_lshlrev_b32_e32 v178, 16, v174
	v_and_b32_e32 v179, 0xffff0000, v174
	v_pk_fma_f32 v[196:197], v[198:199], v[132:133], v[196:197]
	v_pk_fma_f32 v[198:199], v[198:199], v[134:135], v[136:137]
	v_pk_fma_f32 v[232:233], v[186:187], v[4:5], v[232:233]
	v_pk_fma_f32 v[228:229], v[186:187], v[2:3], v[228:229]
	v_pk_fma_f32 v[230:231], v[186:187], v[128:129], v[230:231]
	v_pk_fma_f32 v[148:149], v[178:179], v[16:17], v[148:149]
	v_pk_fma_f32 v[154:155], v[178:179], v[14:15], v[154:155]
	v_pk_fma_f32 v[162:163], v[178:179], v[12:13], v[162:163]
	v_pk_fma_f32 v[236:237], v[178:179], v[10:11], v[170:171]
	v_lshlrev_b32_e32 v170, 16, v176
	v_and_b32_e32 v171, 0xffff0000, v176
	v_pk_fma_f32 v[196:197], v[186:187], v[130:131], v[196:197]
	v_pk_fma_f32 v[198:199], v[186:187], v[132:133], v[198:199]
	v_pk_fma_f32 v[186:187], v[186:187], v[134:135], v[136:137]
	v_pk_fma_f32 v[234:235], v[178:179], v[8:9], v[234:235]
	v_pk_fma_f32 v[232:233], v[178:179], v[6:7], v[232:233]
	v_pk_fma_f32 v[228:229], v[178:179], v[4:5], v[228:229]
	v_pk_fma_f32 v[230:231], v[178:179], v[2:3], v[230:231]
	v_pk_fma_f32 v[148:149], v[170:171], v[90:91], v[148:149]
	v_pk_fma_f32 v[154:155], v[170:171], v[16:17], v[154:155]
	v_pk_fma_f32 v[238:239], v[170:171], v[14:15], v[162:163]
	v_lshlrev_b32_e32 v162, 16, v144
	v_and_b32_e32 v163, 0xffff0000, v144
	v_pk_fma_f32 v[196:197], v[178:179], v[128:129], v[196:197]
	v_pk_fma_f32 v[198:199], v[178:179], v[130:131], v[198:199]
	v_pk_fma_f32 v[186:187], v[178:179], v[132:133], v[186:187]
	v_pk_fma_f32 v[178:179], v[178:179], v[134:135], v[136:137]
	v_pk_fma_f32 v[236:237], v[170:171], v[12:13], v[236:237]
	v_pk_fma_f32 v[234:235], v[170:171], v[10:11], v[234:235]
	v_pk_fma_f32 v[232:233], v[170:171], v[8:9], v[232:233]
	v_pk_fma_f32 v[228:229], v[170:171], v[6:7], v[228:229]
	v_pk_fma_f32 v[230:231], v[170:171], v[4:5], v[230:231]
	v_pk_fma_f32 v[144:145], v[162:163], v[92:93], v[148:149]
	v_pk_fma_f32 v[148:149], v[162:163], v[90:91], v[154:155]
	v_lshlrev_b32_e32 v154, 16, v143
	v_and_b32_e32 v155, 0xffff0000, v143
	v_pk_fma_f32 v[196:197], v[170:171], v[2:3], v[196:197]
	v_pk_fma_f32 v[198:199], v[170:171], v[128:129], v[198:199]
	v_pk_fma_f32 v[186:187], v[170:171], v[130:131], v[186:187]
	v_pk_fma_f32 v[178:179], v[170:171], v[132:133], v[178:179]
	v_pk_fma_f32 v[170:171], v[170:171], v[134:135], v[136:137]
	v_pk_fma_f32 v[238:239], v[162:163], v[16:17], v[238:239]
	v_pk_fma_f32 v[236:237], v[162:163], v[14:15], v[236:237]
	v_pk_fma_f32 v[234:235], v[162:163], v[12:13], v[234:235]
	v_pk_fma_f32 v[232:233], v[162:163], v[10:11], v[232:233]
	v_pk_fma_f32 v[228:229], v[162:163], v[8:9], v[228:229]
	v_pk_fma_f32 v[230:231], v[162:163], v[6:7], v[230:231]
	v_pk_fma_f32 v[144:145], v[154:155], v[94:95], v[144:145]
	v_pk_fma_f32 v[240:241], v[154:155], v[92:93], v[148:149]
	v_lshlrev_b32_e32 v148, 16, v142
	v_and_b32_e32 v149, 0xffff0000, v142
	v_pk_fma_f32 v[196:197], v[162:163], v[4:5], v[196:197]
	v_pk_fma_f32 v[198:199], v[162:163], v[2:3], v[198:199]
	v_pk_fma_f32 v[186:187], v[162:163], v[128:129], v[186:187]
	v_pk_fma_f32 v[178:179], v[162:163], v[130:131], v[178:179]
	v_pk_fma_f32 v[170:171], v[162:163], v[132:133], v[170:171]
	v_pk_fma_f32 v[162:163], v[162:163], v[134:135], v[136:137]
	v_pk_fma_f32 v[238:239], v[154:155], v[90:91], v[238:239]
	v_pk_fma_f32 v[236:237], v[154:155], v[16:17], v[236:237]
	v_pk_fma_f32 v[234:235], v[154:155], v[14:15], v[234:235]
	v_pk_fma_f32 v[232:233], v[154:155], v[12:13], v[232:233]
	v_pk_fma_f32 v[228:229], v[154:155], v[10:11], v[228:229]
	v_pk_fma_f32 v[230:231], v[154:155], v[8:9], v[230:231]
	v_pk_fma_f32 v[142:143], v[148:149], v[96:97], v[144:145]
	v_lshlrev_b32_e32 v144, 16, v141
	v_and_b32_e32 v145, 0xffff0000, v141
	v_pk_fma_f32 v[196:197], v[154:155], v[6:7], v[196:197]
	v_pk_fma_f32 v[198:199], v[154:155], v[4:5], v[198:199]
	v_pk_fma_f32 v[186:187], v[154:155], v[2:3], v[186:187]
	v_pk_fma_f32 v[178:179], v[154:155], v[128:129], v[178:179]
	v_pk_fma_f32 v[170:171], v[154:155], v[130:131], v[170:171]
	v_pk_fma_f32 v[162:163], v[154:155], v[132:133], v[162:163]
	v_pk_fma_f32 v[154:155], v[154:155], v[134:135], v[136:137]
	v_pk_fma_f32 v[134:135], v[148:149], v[134:135], v[136:137]
	v_pk_fma_f32 v[242:243], v[144:145], v[98:99], v[142:143]
	v_lshlrev_b32_e32 v142, 16, v140
	v_and_b32_e32 v143, 0xffff0000, v140
	v_pk_fma_f32 v[154:155], v[148:149], v[132:133], v[154:155]
	v_pk_fma_f32 v[132:133], v[144:145], v[132:133], v[134:135]
	v_lshlrev_b32_e32 v140, 16, v138
	v_and_b32_e32 v141, 0xffff0000, v138
	v_pk_fma_f32 v[162:163], v[148:149], v[130:131], v[162:163]
	v_pk_fma_f32 v[154:155], v[144:145], v[130:131], v[154:155]
	v_pk_fma_f32 v[130:131], v[142:143], v[130:131], v[132:133]
	v_lshlrev_b32_e32 v138, 16, v139
	v_and_b32_e32 v139, 0xffff0000, v139
	v_pk_fma_f32 v[170:171], v[148:149], v[128:129], v[170:171]
	v_pk_fma_f32 v[162:163], v[144:145], v[128:129], v[162:163]
	v_pk_fma_f32 v[154:155], v[142:143], v[128:129], v[154:155]
	v_pk_fma_f32 v[128:129], v[140:141], v[128:129], v[130:131]
	v_and_b32_e32 v147, 0xffff0000, v147
	v_pk_fma_f32 v[178:179], v[148:149], v[2:3], v[178:179]
	v_pk_fma_f32 v[170:171], v[144:145], v[2:3], v[170:171]
	v_pk_fma_f32 v[162:163], v[142:143], v[2:3], v[162:163]
	v_pk_fma_f32 v[154:155], v[140:141], v[2:3], v[154:155]
	v_pk_fma_f32 v[2:3], v[138:139], v[2:3], v[128:129]
	v_pk_fma_f32 v[198:199], v[148:149], v[6:7], v[198:199]
	v_pk_fma_f32 v[2:3], v[146:147], v[4:5], v[2:3]
	v_pk_fma_f32 v[186:187], v[148:149], v[4:5], v[186:187]
	v_pk_fma_f32 v[178:179], v[144:145], v[4:5], v[178:179]
	v_pk_fma_f32 v[170:171], v[142:143], v[4:5], v[170:171]
	v_pk_fma_f32 v[162:163], v[140:141], v[4:5], v[162:163]
	v_pk_fma_f32 v[154:155], v[138:139], v[4:5], v[154:155]
	v_pk_fma_f32 v[2:3], v[150:151], v[6:7], v[2:3]
	v_pk_fma_f32 v[228:229], v[148:149], v[12:13], v[228:229]
	v_pk_fma_f32 v[230:231], v[148:149], v[10:11], v[230:231]
	v_pk_fma_f32 v[196:197], v[148:149], v[8:9], v[196:197]
	v_pk_fma_f32 v[198:199], v[144:145], v[8:9], v[198:199]
	v_pk_fma_f32 v[186:187], v[144:145], v[6:7], v[186:187]
	v_pk_fma_f32 v[178:179], v[142:143], v[6:7], v[178:179]
	v_pk_fma_f32 v[170:171], v[140:141], v[6:7], v[170:171]
	v_pk_fma_f32 v[162:163], v[138:139], v[6:7], v[162:163]
	v_pk_fma_f32 v[154:155], v[146:147], v[6:7], v[154:155]
	v_pk_fma_f32 v[2:3], v[152:153], v[8:9], v[2:3]
	v_pk_fma_f32 v[228:229], v[144:145], v[14:15], v[228:229]
	v_pk_fma_f32 v[230:231], v[144:145], v[12:13], v[230:231]
	v_pk_fma_f32 v[196:197], v[144:145], v[10:11], v[196:197]
	v_pk_fma_f32 v[198:199], v[142:143], v[10:11], v[198:199]
	v_pk_fma_f32 v[186:187], v[142:143], v[8:9], v[186:187]
	v_pk_fma_f32 v[178:179], v[140:141], v[8:9], v[178:179]
	v_pk_fma_f32 v[170:171], v[138:139], v[8:9], v[170:171]
	v_pk_fma_f32 v[162:163], v[146:147], v[8:9], v[162:163]
	v_pk_fma_f32 v[154:155], v[150:151], v[8:9], v[154:155]
	v_pk_fma_f32 v[2:3], v[156:157], v[10:11], v[2:3]
	v_pk_fma_f32 v[232:233], v[148:149], v[14:15], v[232:233]
	v_pk_fma_f32 v[228:229], v[142:143], v[16:17], v[228:229]
	v_pk_fma_f32 v[230:231], v[142:143], v[14:15], v[230:231]
	v_pk_fma_f32 v[196:197], v[142:143], v[12:13], v[196:197]
	v_pk_fma_f32 v[198:199], v[140:141], v[12:13], v[198:199]
	v_pk_fma_f32 v[186:187], v[140:141], v[10:11], v[186:187]
	v_pk_fma_f32 v[178:179], v[138:139], v[10:11], v[178:179]
	v_pk_fma_f32 v[170:171], v[146:147], v[10:11], v[170:171]
	v_pk_fma_f32 v[162:163], v[150:151], v[10:11], v[162:163]
	v_pk_fma_f32 v[154:155], v[152:153], v[10:11], v[154:155]
	v_pk_fma_f32 v[2:3], v[158:159], v[12:13], v[2:3]
	v_pk_fma_f32 v[234:235], v[148:149], v[16:17], v[234:235]
	v_pk_fma_f32 v[232:233], v[144:145], v[16:17], v[232:233]
	v_pk_fma_f32 v[228:229], v[140:141], v[90:91], v[228:229]
	v_pk_fma_f32 v[230:231], v[140:141], v[16:17], v[230:231]
	v_pk_fma_f32 v[196:197], v[140:141], v[14:15], v[196:197]
	v_pk_fma_f32 v[198:199], v[138:139], v[14:15], v[198:199]
	v_pk_fma_f32 v[186:187], v[138:139], v[12:13], v[186:187]
	v_pk_fma_f32 v[178:179], v[146:147], v[12:13], v[178:179]
	v_pk_fma_f32 v[170:171], v[150:151], v[12:13], v[170:171]
	v_pk_fma_f32 v[162:163], v[152:153], v[12:13], v[162:163]
	v_pk_fma_f32 v[154:155], v[156:157], v[12:13], v[154:155]
	v_pk_fma_f32 v[2:3], v[160:161], v[14:15], v[2:3]
	v_pk_fma_f32 v[236:237], v[148:149], v[90:91], v[236:237]
	v_pk_fma_f32 v[234:235], v[144:145], v[90:91], v[234:235]
	v_pk_fma_f32 v[232:233], v[142:143], v[90:91], v[232:233]
	v_pk_fma_f32 v[228:229], v[138:139], v[92:93], v[228:229]
	v_pk_fma_f32 v[230:231], v[138:139], v[90:91], v[230:231]
	v_lshlrev_b32_e32 v166, 16, v167
	v_and_b32_e32 v167, 0xffff0000, v167
	v_pk_fma_f32 v[196:197], v[138:139], v[16:17], v[196:197]
	v_pk_fma_f32 v[198:199], v[146:147], v[16:17], v[198:199]
	v_pk_fma_f32 v[186:187], v[146:147], v[14:15], v[186:187]
	v_pk_fma_f32 v[178:179], v[150:151], v[14:15], v[178:179]
	v_pk_fma_f32 v[170:171], v[152:153], v[14:15], v[170:171]
	v_pk_fma_f32 v[162:163], v[156:157], v[14:15], v[162:163]
	v_pk_fma_f32 v[154:155], v[158:159], v[14:15], v[154:155]
	v_pk_fma_f32 v[2:3], v[164:165], v[16:17], v[2:3]
	v_pk_fma_f32 v[240:241], v[148:149], v[94:95], v[240:241]
	v_pk_fma_f32 v[238:239], v[148:149], v[92:93], v[238:239]
	v_pk_fma_f32 v[236:237], v[144:145], v[92:93], v[236:237]
	v_pk_fma_f32 v[234:235], v[142:143], v[92:93], v[234:235]
	v_pk_fma_f32 v[232:233], v[140:141], v[92:93], v[232:233]
	v_pk_fma_f32 v[228:229], v[146:147], v[94:95], v[228:229]
	v_pk_fma_f32 v[230:231], v[146:147], v[92:93], v[230:231]
	v_lshlrev_b32_e32 v168, 16, v169
	v_and_b32_e32 v169, 0xffff0000, v169
	v_pk_fma_f32 v[196:197], v[146:147], v[90:91], v[196:197]
	v_pk_fma_f32 v[198:199], v[150:151], v[90:91], v[198:199]
	v_pk_fma_f32 v[186:187], v[150:151], v[16:17], v[186:187]
	v_pk_fma_f32 v[178:179], v[152:153], v[16:17], v[178:179]
	v_pk_fma_f32 v[170:171], v[156:157], v[16:17], v[170:171]
	v_pk_fma_f32 v[162:163], v[158:159], v[16:17], v[162:163]
	v_pk_fma_f32 v[154:155], v[160:161], v[16:17], v[154:155]
	v_pk_fma_f32 v[2:3], v[166:167], v[90:91], v[2:3]
	v_pk_fma_f32 v[240:241], v[144:145], v[96:97], v[240:241]
	v_pk_fma_f32 v[238:239], v[144:145], v[94:95], v[238:239]
	v_pk_fma_f32 v[236:237], v[142:143], v[94:95], v[236:237]
	v_pk_fma_f32 v[234:235], v[140:141], v[94:95], v[234:235]
	v_pk_fma_f32 v[232:233], v[138:139], v[94:95], v[232:233]
	v_pk_fma_f32 v[228:229], v[150:151], v[96:97], v[228:229]
	v_pk_fma_f32 v[230:231], v[150:151], v[94:95], v[230:231]
	v_lshlrev_b32_e32 v172, 16, v173
	v_and_b32_e32 v173, 0xffff0000, v173
	v_pk_fma_f32 v[196:197], v[150:151], v[92:93], v[196:197]
	v_pk_fma_f32 v[198:199], v[152:153], v[92:93], v[198:199]
	v_pk_fma_f32 v[186:187], v[152:153], v[90:91], v[186:187]
	v_pk_fma_f32 v[178:179], v[156:157], v[90:91], v[178:179]
	v_pk_fma_f32 v[170:171], v[158:159], v[90:91], v[170:171]
	v_pk_fma_f32 v[162:163], v[160:161], v[90:91], v[162:163]
	v_pk_fma_f32 v[154:155], v[164:165], v[90:91], v[154:155]
	v_pk_fma_f32 v[2:3], v[168:169], v[92:93], v[2:3]
	v_pk_fma_f32 v[240:241], v[142:143], v[98:99], v[240:241]
	v_pk_fma_f32 v[238:239], v[142:143], v[96:97], v[238:239]
	v_pk_fma_f32 v[236:237], v[140:141], v[96:97], v[236:237]
	v_pk_fma_f32 v[234:235], v[138:139], v[96:97], v[234:235]
	v_pk_fma_f32 v[232:233], v[146:147], v[96:97], v[232:233]
	v_pk_fma_f32 v[228:229], v[152:153], v[98:99], v[228:229]
	v_pk_fma_f32 v[230:231], v[152:153], v[96:97], v[230:231]
	v_lshlrev_b32_e32 v174, 16, v175
	v_and_b32_e32 v175, 0xffff0000, v175
	v_pk_fma_f32 v[196:197], v[152:153], v[94:95], v[196:197]
	v_pk_fma_f32 v[198:199], v[156:157], v[94:95], v[198:199]
	v_pk_fma_f32 v[186:187], v[156:157], v[92:93], v[186:187]
	v_pk_fma_f32 v[178:179], v[158:159], v[92:93], v[178:179]
	v_pk_fma_f32 v[170:171], v[160:161], v[92:93], v[170:171]
	v_pk_fma_f32 v[162:163], v[164:165], v[92:93], v[162:163]
	v_pk_fma_f32 v[154:155], v[166:167], v[92:93], v[154:155]
	v_pk_fma_f32 v[2:3], v[172:173], v[94:95], v[2:3]
	v_pk_fma_f32 v[242:243], v[142:143], v[100:101], v[242:243]
	v_pk_fma_f32 v[240:241], v[140:141], v[100:101], v[240:241]
	v_pk_fma_f32 v[238:239], v[140:141], v[98:99], v[238:239]
	v_pk_fma_f32 v[236:237], v[138:139], v[98:99], v[236:237]
	v_pk_fma_f32 v[234:235], v[146:147], v[98:99], v[234:235]
	v_pk_fma_f32 v[232:233], v[150:151], v[98:99], v[232:233]
	v_pk_fma_f32 v[228:229], v[156:157], v[100:101], v[228:229]
	v_pk_fma_f32 v[230:231], v[156:157], v[98:99], v[230:231]
	v_lshlrev_b32_e32 v176, 16, v177
	v_and_b32_e32 v177, 0xffff0000, v177
	v_pk_fma_f32 v[196:197], v[156:157], v[96:97], v[196:197]
	v_pk_fma_f32 v[198:199], v[158:159], v[96:97], v[198:199]
	v_pk_fma_f32 v[186:187], v[158:159], v[94:95], v[186:187]
	v_pk_fma_f32 v[178:179], v[160:161], v[94:95], v[178:179]
	v_pk_fma_f32 v[170:171], v[164:165], v[94:95], v[170:171]
	v_pk_fma_f32 v[162:163], v[166:167], v[94:95], v[162:163]
	v_pk_fma_f32 v[154:155], v[168:169], v[94:95], v[154:155]
	v_pk_fma_f32 v[2:3], v[174:175], v[96:97], v[2:3]
	v_pk_fma_f32 v[242:243], v[140:141], v[102:103], v[242:243]
	v_pk_fma_f32 v[240:241], v[138:139], v[102:103], v[240:241]
	v_pk_fma_f32 v[238:239], v[138:139], v[100:101], v[238:239]
	v_pk_fma_f32 v[236:237], v[146:147], v[100:101], v[236:237]
	v_pk_fma_f32 v[234:235], v[150:151], v[100:101], v[234:235]
	v_pk_fma_f32 v[232:233], v[152:153], v[100:101], v[232:233]
	v_pk_fma_f32 v[228:229], v[158:159], v[102:103], v[228:229]
	v_pk_fma_f32 v[230:231], v[158:159], v[100:101], v[230:231]
	v_pk_fma_f32 v[196:197], v[158:159], v[98:99], v[196:197]
	v_pk_fma_f32 v[198:199], v[160:161], v[98:99], v[198:199]
	v_pk_fma_f32 v[186:187], v[160:161], v[96:97], v[186:187]
	v_pk_fma_f32 v[178:179], v[164:165], v[96:97], v[178:179]
	v_pk_fma_f32 v[170:171], v[166:167], v[96:97], v[170:171]
	v_pk_fma_f32 v[162:163], v[168:169], v[96:97], v[162:163]
	v_pk_fma_f32 v[154:155], v[172:173], v[96:97], v[154:155]
	v_pk_fma_f32 v[2:3], v[176:177], v[98:99], v[2:3]
	v_pk_fma_f32 v[242:243], v[138:139], v[104:105], v[242:243]
	v_pk_fma_f32 v[240:241], v[146:147], v[104:105], v[240:241]
	v_pk_fma_f32 v[238:239], v[146:147], v[102:103], v[238:239]
	v_pk_fma_f32 v[236:237], v[150:151], v[102:103], v[236:237]
	v_pk_fma_f32 v[234:235], v[152:153], v[102:103], v[234:235]
	v_pk_fma_f32 v[232:233], v[156:157], v[102:103], v[232:233]
	v_pk_fma_f32 v[228:229], v[160:161], v[104:105], v[228:229]
	v_pk_fma_f32 v[230:231], v[160:161], v[102:103], v[230:231]
	v_pk_fma_f32 v[196:197], v[160:161], v[100:101], v[196:197]
	v_pk_fma_f32 v[198:199], v[164:165], v[100:101], v[198:199]
	v_pk_fma_f32 v[186:187], v[164:165], v[98:99], v[186:187]
	v_pk_fma_f32 v[178:179], v[166:167], v[98:99], v[178:179]
	v_pk_fma_f32 v[170:171], v[168:169], v[98:99], v[170:171]
	v_pk_fma_f32 v[162:163], v[172:173], v[98:99], v[162:163]
	v_pk_fma_f32 v[154:155], v[174:175], v[98:99], v[154:155]
	v_pk_fma_f32 v[2:3], v[180:181], v[100:101], v[2:3]
	v_pk_fma_f32 v[242:243], v[146:147], v[106:107], v[242:243]
	v_pk_fma_f32 v[240:241], v[150:151], v[106:107], v[240:241]
	v_pk_fma_f32 v[238:239], v[150:151], v[104:105], v[238:239]
	v_pk_fma_f32 v[236:237], v[152:153], v[104:105], v[236:237]
	v_pk_fma_f32 v[234:235], v[156:157], v[104:105], v[234:235]
	v_pk_fma_f32 v[232:233], v[158:159], v[104:105], v[232:233]
	v_pk_fma_f32 v[228:229], v[164:165], v[106:107], v[228:229]
	v_pk_fma_f32 v[230:231], v[164:165], v[104:105], v[230:231]
	v_pk_fma_f32 v[196:197], v[164:165], v[102:103], v[196:197]
	v_pk_fma_f32 v[198:199], v[166:167], v[102:103], v[198:199]
	v_pk_fma_f32 v[186:187], v[166:167], v[100:101], v[186:187]
	v_pk_fma_f32 v[178:179], v[168:169], v[100:101], v[178:179]
	v_pk_fma_f32 v[170:171], v[172:173], v[100:101], v[170:171]
	v_pk_fma_f32 v[162:163], v[174:175], v[100:101], v[162:163]
	v_pk_fma_f32 v[154:155], v[176:177], v[100:101], v[154:155]
	v_pk_fma_f32 v[2:3], v[182:183], v[102:103], v[2:3]
	v_pk_fma_f32 v[242:243], v[150:151], v[108:109], v[242:243]
	v_pk_fma_f32 v[240:241], v[152:153], v[108:109], v[240:241]
	v_pk_fma_f32 v[238:239], v[152:153], v[106:107], v[238:239]
	v_pk_fma_f32 v[236:237], v[156:157], v[106:107], v[236:237]
	v_pk_fma_f32 v[234:235], v[158:159], v[106:107], v[234:235]
	v_pk_fma_f32 v[232:233], v[160:161], v[106:107], v[232:233]
	v_pk_fma_f32 v[228:229], v[166:167], v[108:109], v[228:229]
	v_add_u32_e32 v146, v215, v226
	v_add_u32_e32 v146, 0x2000, v146
	v_ashrrev_i32_e32 v147, 31, v146
	v_lshlrev_b64 v[144:145], 10, v[146:147]
	v_lshl_add_u64 v[144:145], v[86:87], 0, v[144:145]
	global_load_dwordx2 v[128:129], v[144:145], off
	global_load_dwordx2 v[130:131], v[144:145], off offset:512
	global_load_dwordx2 v[132:133], v[144:145], off offset:1024
	global_load_dwordx2 v[134:135], v[144:145], off offset:1536
	global_load_dwordx2 v[136:137], v[144:145], off offset:2048
	global_load_dwordx2 v[138:139], v[144:145], off offset:2560
	global_load_dwordx2 v[140:141], v[144:145], off offset:3072
	global_load_dwordx2 v[142:143], v[144:145], off offset:3584
	v_pk_fma_f32 v[230:231], v[166:167], v[106:107], v[230:231]
	v_pk_fma_f32 v[196:197], v[166:167], v[104:105], v[196:197]
	v_pk_fma_f32 v[198:199], v[168:169], v[104:105], v[198:199]
	v_pk_fma_f32 v[186:187], v[168:169], v[102:103], v[186:187]
	v_pk_fma_f32 v[178:179], v[172:173], v[102:103], v[178:179]
	v_pk_fma_f32 v[170:171], v[174:175], v[102:103], v[170:171]
	v_pk_fma_f32 v[162:163], v[176:177], v[102:103], v[162:163]
	v_pk_fma_f32 v[154:155], v[180:181], v[102:103], v[154:155]
	v_pk_fma_f32 v[2:3], v[184:185], v[104:105], v[2:3]
	v_pk_fma_f32 v[242:243], v[152:153], v[110:111], v[242:243]
	v_pk_fma_f32 v[240:241], v[156:157], v[110:111], v[240:241]
	v_pk_fma_f32 v[238:239], v[156:157], v[108:109], v[238:239]
	v_pk_fma_f32 v[236:237], v[158:159], v[108:109], v[236:237]
	v_pk_fma_f32 v[234:235], v[160:161], v[108:109], v[234:235]
	v_pk_fma_f32 v[232:233], v[164:165], v[108:109], v[232:233]
	v_pk_fma_f32 v[228:229], v[168:169], v[110:111], v[228:229]
	v_pk_fma_f32 v[230:231], v[168:169], v[108:109], v[230:231]
	v_pk_fma_f32 v[196:197], v[168:169], v[106:107], v[196:197]
	v_pk_fma_f32 v[198:199], v[172:173], v[106:107], v[198:199]
	v_pk_fma_f32 v[186:187], v[172:173], v[104:105], v[186:187]
	v_pk_fma_f32 v[178:179], v[174:175], v[104:105], v[178:179]
	v_pk_fma_f32 v[170:171], v[176:177], v[104:105], v[170:171]
	v_pk_fma_f32 v[162:163], v[180:181], v[104:105], v[162:163]
	v_pk_fma_f32 v[154:155], v[182:183], v[104:105], v[154:155]
	v_pk_fma_f32 v[2:3], v[188:189], v[106:107], v[2:3]
	v_pk_fma_f32 v[242:243], v[156:157], v[112:113], v[242:243]
	v_pk_fma_f32 v[240:241], v[158:159], v[112:113], v[240:241]
	v_pk_fma_f32 v[238:239], v[158:159], v[110:111], v[238:239]
	v_pk_fma_f32 v[236:237], v[160:161], v[110:111], v[236:237]
	v_pk_fma_f32 v[234:235], v[164:165], v[110:111], v[234:235]
	v_pk_fma_f32 v[232:233], v[166:167], v[110:111], v[232:233]
	v_pk_fma_f32 v[228:229], v[172:173], v[112:113], v[228:229]
	v_pk_fma_f32 v[230:231], v[172:173], v[110:111], v[230:231]
	v_pk_fma_f32 v[196:197], v[172:173], v[108:109], v[196:197]
	v_pk_fma_f32 v[198:199], v[174:175], v[108:109], v[198:199]
	v_pk_fma_f32 v[186:187], v[174:175], v[106:107], v[186:187]
	v_pk_fma_f32 v[178:179], v[176:177], v[106:107], v[178:179]
	v_pk_fma_f32 v[170:171], v[180:181], v[106:107], v[170:171]
	v_pk_fma_f32 v[162:163], v[182:183], v[106:107], v[162:163]
	v_pk_fma_f32 v[154:155], v[184:185], v[106:107], v[154:155]
	v_pk_fma_f32 v[2:3], v[190:191], v[108:109], v[2:3]
	v_pk_fma_f32 v[242:243], v[158:159], v[114:115], v[242:243]
	v_pk_fma_f32 v[240:241], v[160:161], v[114:115], v[240:241]
	v_pk_fma_f32 v[238:239], v[160:161], v[112:113], v[238:239]
	v_pk_fma_f32 v[236:237], v[164:165], v[112:113], v[236:237]
	v_pk_fma_f32 v[234:235], v[166:167], v[112:113], v[234:235]
	v_pk_fma_f32 v[232:233], v[168:169], v[112:113], v[232:233]
	v_pk_fma_f32 v[228:229], v[174:175], v[114:115], v[228:229]
	v_pk_fma_f32 v[230:231], v[174:175], v[112:113], v[230:231]
	v_pk_fma_f32 v[196:197], v[174:175], v[110:111], v[196:197]
	v_pk_fma_f32 v[198:199], v[176:177], v[110:111], v[198:199]
	v_pk_fma_f32 v[186:187], v[176:177], v[108:109], v[186:187]
	v_pk_fma_f32 v[178:179], v[180:181], v[108:109], v[178:179]
	v_pk_fma_f32 v[170:171], v[182:183], v[108:109], v[170:171]
	v_pk_fma_f32 v[162:163], v[184:185], v[108:109], v[162:163]
	v_pk_fma_f32 v[154:155], v[188:189], v[108:109], v[154:155]
	v_pk_fma_f32 v[2:3], v[192:193], v[110:111], v[2:3]
	v_pk_fma_f32 v[242:243], v[160:161], v[116:117], v[242:243]
	v_pk_fma_f32 v[240:241], v[164:165], v[116:117], v[240:241]
	v_pk_fma_f32 v[238:239], v[164:165], v[114:115], v[238:239]
	v_pk_fma_f32 v[236:237], v[166:167], v[114:115], v[236:237]
	v_pk_fma_f32 v[234:235], v[168:169], v[114:115], v[234:235]
	v_pk_fma_f32 v[232:233], v[172:173], v[114:115], v[232:233]
	v_pk_fma_f32 v[228:229], v[176:177], v[116:117], v[228:229]
	v_pk_fma_f32 v[230:231], v[176:177], v[114:115], v[230:231]
	v_pk_fma_f32 v[196:197], v[176:177], v[112:113], v[196:197]
	v_pk_fma_f32 v[198:199], v[180:181], v[112:113], v[198:199]
	v_pk_fma_f32 v[186:187], v[180:181], v[110:111], v[186:187]
	v_pk_fma_f32 v[178:179], v[182:183], v[110:111], v[178:179]
	v_pk_fma_f32 v[170:171], v[184:185], v[110:111], v[170:171]
	v_pk_fma_f32 v[162:163], v[188:189], v[110:111], v[162:163]
	v_pk_fma_f32 v[154:155], v[190:191], v[110:111], v[154:155]
	v_pk_fma_f32 v[2:3], v[194:195], v[112:113], v[2:3]
	v_pk_fma_f32 v[242:243], v[164:165], v[118:119], v[242:243]
	v_pk_fma_f32 v[240:241], v[166:167], v[118:119], v[240:241]
	v_pk_fma_f32 v[238:239], v[166:167], v[116:117], v[238:239]
	v_pk_fma_f32 v[236:237], v[168:169], v[116:117], v[236:237]
	v_pk_fma_f32 v[234:235], v[172:173], v[116:117], v[234:235]
	v_pk_fma_f32 v[232:233], v[174:175], v[116:117], v[232:233]
	v_pk_fma_f32 v[228:229], v[180:181], v[118:119], v[228:229]
	v_pk_fma_f32 v[230:231], v[180:181], v[116:117], v[230:231]
	v_pk_fma_f32 v[196:197], v[180:181], v[114:115], v[196:197]
	v_pk_fma_f32 v[198:199], v[182:183], v[114:115], v[198:199]
	v_pk_fma_f32 v[186:187], v[182:183], v[112:113], v[186:187]
	v_pk_fma_f32 v[178:179], v[184:185], v[112:113], v[178:179]
	v_pk_fma_f32 v[170:171], v[188:189], v[112:113], v[170:171]
	v_pk_fma_f32 v[162:163], v[190:191], v[112:113], v[162:163]
	v_pk_fma_f32 v[154:155], v[192:193], v[112:113], v[154:155]
	v_pk_fma_f32 v[2:3], v[200:201], v[114:115], v[2:3]
	v_pk_fma_f32 v[242:243], v[166:167], v[120:121], v[242:243]
	v_pk_fma_f32 v[240:241], v[168:169], v[120:121], v[240:241]
	v_pk_fma_f32 v[238:239], v[168:169], v[118:119], v[238:239]
	v_pk_fma_f32 v[236:237], v[172:173], v[118:119], v[236:237]
	v_pk_fma_f32 v[234:235], v[174:175], v[118:119], v[234:235]
	v_pk_fma_f32 v[232:233], v[176:177], v[118:119], v[232:233]
	v_pk_fma_f32 v[228:229], v[182:183], v[120:121], v[228:229]
	v_pk_fma_f32 v[230:231], v[182:183], v[118:119], v[230:231]
	v_pk_fma_f32 v[196:197], v[182:183], v[116:117], v[196:197]
	v_pk_fma_f32 v[198:199], v[184:185], v[116:117], v[198:199]
	v_pk_fma_f32 v[186:187], v[184:185], v[114:115], v[186:187]
	v_pk_fma_f32 v[178:179], v[188:189], v[114:115], v[178:179]
	v_pk_fma_f32 v[170:171], v[190:191], v[114:115], v[170:171]
	v_pk_fma_f32 v[162:163], v[192:193], v[114:115], v[162:163]
	v_pk_fma_f32 v[154:155], v[194:195], v[114:115], v[154:155]
	v_pk_fma_f32 v[2:3], v[202:203], v[116:117], v[2:3]
	v_pk_fma_f32 v[242:243], v[168:169], v[122:123], v[242:243]
	v_pk_fma_f32 v[240:241], v[172:173], v[122:123], v[240:241]
	v_pk_fma_f32 v[238:239], v[172:173], v[120:121], v[238:239]
	v_pk_fma_f32 v[236:237], v[174:175], v[120:121], v[236:237]
	v_pk_fma_f32 v[234:235], v[176:177], v[120:121], v[234:235]
	v_pk_fma_f32 v[232:233], v[180:181], v[120:121], v[232:233]
	v_pk_fma_f32 v[228:229], v[184:185], v[122:123], v[228:229]
	v_pk_fma_f32 v[230:231], v[184:185], v[120:121], v[230:231]
	v_pk_fma_f32 v[196:197], v[184:185], v[118:119], v[196:197]
	v_pk_fma_f32 v[198:199], v[188:189], v[118:119], v[198:199]
	v_pk_fma_f32 v[186:187], v[188:189], v[116:117], v[186:187]
	v_pk_fma_f32 v[178:179], v[190:191], v[116:117], v[178:179]
	v_lshlrev_b32_e32 v206, 16, v207
	v_and_b32_e32 v207, 0xffff0000, v207
	v_pk_fma_f32 v[170:171], v[192:193], v[116:117], v[170:171]
	v_pk_fma_f32 v[162:163], v[194:195], v[116:117], v[162:163]
	v_pk_fma_f32 v[154:155], v[200:201], v[116:117], v[154:155]
	v_pk_fma_f32 v[2:3], v[204:205], v[118:119], v[2:3]
	v_pk_fma_f32 v[242:243], v[172:173], v[124:125], v[242:243]
	v_pk_fma_f32 v[240:241], v[174:175], v[124:125], v[240:241]
	v_pk_fma_f32 v[238:239], v[174:175], v[122:123], v[238:239]
	v_pk_fma_f32 v[236:237], v[176:177], v[122:123], v[236:237]
	v_pk_fma_f32 v[234:235], v[180:181], v[122:123], v[234:235]
	v_pk_fma_f32 v[232:233], v[182:183], v[122:123], v[232:233]
	v_pk_fma_f32 v[228:229], v[188:189], v[124:125], v[228:229]
	v_pk_fma_f32 v[230:231], v[188:189], v[122:123], v[230:231]
	v_pk_fma_f32 v[196:197], v[188:189], v[120:121], v[196:197]
	v_pk_fma_f32 v[198:199], v[190:191], v[120:121], v[198:199]
	v_pk_fma_f32 v[186:187], v[190:191], v[118:119], v[186:187]
	v_pk_fma_f32 v[178:179], v[192:193], v[118:119], v[178:179]
	v_pk_fma_f32 v[170:171], v[194:195], v[118:119], v[170:171]
	v_lshlrev_b32_e32 v208, 16, v209
	v_and_b32_e32 v209, 0xffff0000, v209
	v_pk_fma_f32 v[162:163], v[200:201], v[118:119], v[162:163]
	v_pk_fma_f32 v[154:155], v[202:203], v[118:119], v[154:155]
	v_pk_fma_f32 v[2:3], v[206:207], v[120:121], v[2:3]
	v_pk_fma_f32 v[242:243], v[174:175], v[126:127], v[242:243]
	v_pk_fma_f32 v[240:241], v[176:177], v[126:127], v[240:241]
	v_pk_fma_f32 v[238:239], v[176:177], v[124:125], v[238:239]
	v_pk_fma_f32 v[236:237], v[180:181], v[124:125], v[236:237]
	v_pk_fma_f32 v[234:235], v[182:183], v[124:125], v[234:235]
	v_pk_fma_f32 v[232:233], v[184:185], v[124:125], v[232:233]
	v_pk_fma_f32 v[228:229], v[190:191], v[126:127], v[228:229]
	v_pk_fma_f32 v[230:231], v[190:191], v[124:125], v[230:231]
	v_pk_fma_f32 v[196:197], v[190:191], v[122:123], v[196:197]
	v_pk_fma_f32 v[198:199], v[192:193], v[122:123], v[198:199]
	v_pk_fma_f32 v[186:187], v[192:193], v[120:121], v[186:187]
	v_pk_fma_f32 v[178:179], v[194:195], v[120:121], v[178:179]
	v_pk_fma_f32 v[170:171], v[200:201], v[120:121], v[170:171]
	v_pk_fma_f32 v[162:163], v[202:203], v[120:121], v[162:163]
	v_lshlrev_b32_e32 v210, 16, v211
	v_and_b32_e32 v211, 0xffff0000, v211
	v_pk_fma_f32 v[154:155], v[204:205], v[120:121], v[154:155]
	v_pk_fma_f32 v[2:3], v[208:209], v[122:123], v[2:3]
	v_add_u32_e32 v120, v215, v226
	v_pk_fma_f32 v[238:239], v[180:181], v[126:127], v[238:239]
	v_pk_fma_f32 v[236:237], v[182:183], v[126:127], v[236:237]
	v_pk_fma_f32 v[234:235], v[184:185], v[126:127], v[234:235]
	v_pk_fma_f32 v[232:233], v[188:189], v[126:127], v[232:233]
	v_pk_fma_f32 v[230:231], v[192:193], v[126:127], v[230:231]
	ds_write2st64_b64 v214, v[242:243], v[240:241] offset1:4
	ds_write2st64_b64 v214, v[238:239], v[236:237] offset0:8 offset1:12
	ds_write2st64_b64 v214, v[234:235], v[232:233] offset0:16 offset1:20
	ds_write2st64_b64 v214, v[228:229], v[230:231] offset0:24 offset1:28
	v_pk_fma_f32 v[196:197], v[192:193], v[124:125], v[196:197]
	v_pk_fma_f32 v[198:199], v[194:195], v[124:125], v[198:199]
	v_pk_fma_f32 v[186:187], v[194:195], v[122:123], v[186:187]
	v_pk_fma_f32 v[178:179], v[200:201], v[122:123], v[178:179]
	v_pk_fma_f32 v[170:171], v[202:203], v[122:123], v[170:171]
	v_pk_fma_f32 v[162:163], v[204:205], v[122:123], v[162:163]
	v_pk_fma_f32 v[154:155], v[206:207], v[122:123], v[154:155]
	v_lshlrev_b32_e32 v228, 16, v227
	v_and_b32_e32 v229, 0xffff0000, v227
	v_pk_fma_f32 v[2:3], v[210:211], v[124:125], v[2:3]
	v_add_u32_e32 v98, 0x2000, v120
	v_pk_fma_f32 v[196:197], v[194:195], v[126:127], v[196:197]
	v_pk_fma_f32 v[198:199], v[200:201], v[126:127], v[198:199]
	v_pk_fma_f32 v[186:187], v[200:201], v[124:125], v[186:187]
	v_pk_fma_f32 v[178:179], v[202:203], v[124:125], v[178:179]
	v_pk_fma_f32 v[170:171], v[204:205], v[124:125], v[170:171]
	v_pk_fma_f32 v[162:163], v[206:207], v[124:125], v[162:163]
	v_pk_fma_f32 v[154:155], v[208:209], v[124:125], v[154:155]
	v_pk_fma_f32 v[2:3], v[228:229], v[126:127], v[2:3]
	v_ashrrev_i32_e32 v99, 31, v98
	v_pk_fma_f32 v[186:187], v[202:203], v[126:127], v[186:187]
	v_pk_fma_f32 v[178:179], v[204:205], v[126:127], v[178:179]
	v_pk_fma_f32 v[170:171], v[206:207], v[126:127], v[170:171]
	v_pk_fma_f32 v[162:163], v[208:209], v[126:127], v[162:163]
	v_pk_fma_f32 v[154:155], v[210:211], v[126:127], v[154:155]
	ds_write2st64_b64 v214, v[196:197], v[198:199] offset0:32 offset1:36
	ds_write2st64_b64 v214, v[186:187], v[178:179] offset0:40 offset1:44
	ds_write2st64_b64 v214, v[170:171], v[162:163] offset0:48 offset1:52
	ds_write2st64_b64 v214, v[154:155], v[2:3] offset0:56 offset1:60
	v_lshlrev_b64 v[2:3], 10, v[98:99]
	v_lshl_add_u64 v[2:3], v[86:87], 0, v[2:3]
	s_waitcnt lgkmcnt(0)
	s_barrier
	v_add_u32_e32 v226, s9, v226
	s_waitcnt vmcnt(7)
	v_lshlrev_b32_e32 v100, 16, v128
	v_and_b32_e32 v101, 0xffff0000, v128
	v_lshlrev_b32_e32 v102, 16, v129
	v_and_b32_e32 v103, 0xffff0000, v129
	s_waitcnt vmcnt(6)
	v_lshlrev_b32_e32 v104, 16, v130
	v_and_b32_e32 v105, 0xffff0000, v130
	v_lshlrev_b32_e32 v106, 16, v131
	v_and_b32_e32 v107, 0xffff0000, v131
	global_load_dwordx4 v[2:5], v[82:83], off offset:1024
	global_load_dwordx4 v[6:9], v[84:85], off offset:1024
	ds_read_b128 v[90:93], v216 offset:1024
	global_load_dwordx4 v[10:13], v[82:83], off
	global_load_dwordx4 v[14:17], v[84:85], off
	ds_read_b128 v[94:97], v216
	s_waitcnt lgkmcnt(1)
	v_pk_mul_f32 v[110:111], v[90:91], v[90:91]
	v_pk_mul_f32 v[108:109], v[92:93], v[92:93]
	s_waitcnt lgkmcnt(0)
	v_mov_b32_e32 v114, v94
	v_mov_b32_e32 v115, v96
	v_pk_mul_f32 v[114:115], v[114:115], v[114:115]
	v_pk_mul_f32 v[116:117], v[94:95], v[94:95]
	v_mov_b32_e32 v118, v114
	v_mov_b32_e32 v119, v94
	v_mov_b32_e32 v116, v117
	v_mov_b32_e32 v117, v95
	v_pk_mul_f32 v[112:113], v[96:97], v[96:97]
	v_pk_add_f32 v[116:117], v[118:119], v[116:117]
	v_pk_mov_b32 v[114:115], v[114:115], v[96:97] op_sel:[1,0]
	v_mov_b32_e32 v112, v113
	v_pk_add_f32 v[114:115], v[116:117], v[114:115]
	v_mov_b32_e32 v113, v97
	v_pk_add_f32 v[112:113], v[114:115], v[112:113]
	v_mov_b32_e32 v114, v110
	v_mov_b32_e32 v115, v90
	v_pk_add_f32 v[112:113], v[112:113], v[114:115]
	v_mov_b32_e32 v110, v111
	v_mov_b32_e32 v111, v91
	v_pk_add_f32 v[110:111], v[112:113], v[110:111]
	v_mov_b32_e32 v112, v108
	v_mov_b32_e32 v113, v92
	v_pk_add_f32 v[110:111], v[110:111], v[112:113]
	v_mov_b32_e32 v108, v109
	v_mov_b32_e32 v109, v93
	v_pk_add_f32 v[108:109], v[110:111], v[108:109]
	ds_bpermute_b32 v111, v217, v109
	ds_bpermute_b32 v110, v217, v108
	s_waitcnt lgkmcnt(0)
	v_pk_add_f32 v[108:109], v[108:109], v[110:111]
	ds_bpermute_b32 v111, v218, v109
	ds_bpermute_b32 v110, v218, v108
	s_waitcnt lgkmcnt(0)
	v_pk_add_f32 v[108:109], v[108:109], v[110:111]
	ds_bpermute_b32 v111, v219, v109
	ds_bpermute_b32 v110, v219, v108
	s_waitcnt lgkmcnt(0)
	v_pk_add_f32 v[108:109], v[108:109], v[110:111]
	ds_bpermute_b32 v111, v220, v109
	ds_bpermute_b32 v110, v220, v108
	s_waitcnt lgkmcnt(0)
	v_pk_add_f32 v[108:109], v[108:109], v[110:111]
	ds_bpermute_b32 v111, v221, v109
	ds_bpermute_b32 v110, v221, v108
	s_waitcnt lgkmcnt(0)
	v_pk_add_f32 v[108:109], v[108:109], v[110:111]
	ds_bpermute_b32 v111, v222, v109
	ds_bpermute_b32 v110, v222, v108
	s_waitcnt lgkmcnt(0)
	v_pk_add_f32 v[108:109], v[108:109], v[110:111]
	s_nop 0
	v_pk_mul_f32 v[108:109], v[108:109], s[6:7] op_sel_hi:[1,0]
	s_nop 0
	v_fma_f32 v110, -v109, v109, v108
	v_max_f32_e32 v110, 0, v110
	v_add_f32_e32 v110, 0x358637bd, v110
	v_cmp_gt_f32_e32 vcc, s22, v110
	v_mul_f32_e32 v111, 0x4b800000, v110
	v_pk_add_f32 v[94:95], v[94:95], v[108:109] op_sel:[0,1] neg_lo:[0,1] neg_hi:[0,1]
	v_cndmask_b32_e32 v110, v110, v111, vcc
	v_rsq_f32_e32 v110, v110
	v_pk_add_f32 v[96:97], v[96:97], v[108:109] op_sel:[0,1] neg_lo:[0,1] neg_hi:[0,1]
	v_pk_add_f32 v[90:91], v[90:91], v[108:109] op_sel:[0,1] neg_lo:[0,1] neg_hi:[0,1]
	v_pk_add_f32 v[92:93], v[92:93], v[108:109] op_sel:[0,1] neg_lo:[0,1] neg_hi:[0,1]
	v_mul_f32_e32 v111, 0x45800000, v110
	v_cndmask_b32_e32 v110, v110, v111, vcc
	v_pk_mul_f32 v[94:95], v[94:95], v[110:111] op_sel_hi:[1,0]
	s_waitcnt vmcnt(0)
	v_pk_fma_f32 v[94:95], v[10:11], v[94:95], v[14:15]
	s_nop 0
	v_mul_f32_e32 v111, 0xbfb8aa3b, v94
	v_exp_f32_e32 v111, v111
	s_nop 0
	v_add_f32_e32 v111, 1.0, v111
	v_rcp_f32_e32 v112, v111
	v_mul_f32_e32 v111, 0xbfb8aa3b, v95
	v_exp_f32_e32 v111, v111
	s_nop 0
	v_add_f32_e32 v111, 1.0, v111
	v_rcp_f32_e32 v113, v111
	v_pk_mul_f32 v[96:97], v[96:97], v[110:111] op_sel_hi:[1,0]
	v_pk_mul_f32 v[90:91], v[90:91], v[110:111] op_sel_hi:[1,0]
	v_pk_fma_f32 v[96:97], v[12:13], v[96:97], v[16:17]
	v_pk_mul_f32 v[94:95], v[94:95], v[112:113]
	v_pk_fma_f32 v[90:91], v[2:3], v[90:91], v[6:7]
	v_pk_mul_f32 v[94:95], v[94:95], v[100:101]
	v_pk_mul_f32 v[92:93], v[92:93], v[110:111] op_sel_hi:[1,0]
	v_cvt_pk_bf16_f32 v94, v94, v95
	v_mul_f32_e32 v95, 0xbfb8aa3b, v96
	v_exp_f32_e32 v95, v95
	v_pk_fma_f32 v[92:93], v[4:5], v[92:93], v[8:9]
	v_add_f32_e32 v95, 1.0, v95
	v_rcp_f32_e32 v100, v95
	v_mul_f32_e32 v95, 0xbfb8aa3b, v97
	v_exp_f32_e32 v95, v95
	s_nop 0
	v_add_f32_e32 v95, 1.0, v95
	v_rcp_f32_e32 v101, v95
	s_nop 0
	v_pk_mul_f32 v[96:97], v[96:97], v[100:101]
	s_nop 0
	v_pk_mul_f32 v[96:97], v[96:97], v[102:103]
	s_nop 0
	v_cvt_pk_bf16_f32 v95, v96, v97
	v_mul_f32_e32 v96, 0xbfb8aa3b, v90
	v_mul_f32_e32 v97, 0xbfb8aa3b, v91
	v_exp_f32_e32 v96, v96
	v_exp_f32_e32 v97, v97
	v_add_f32_e32 v96, 1.0, v96
	v_add_f32_e32 v97, 1.0, v97
	v_rcp_f32_e32 v96, v96
	v_rcp_f32_e32 v97, v97
	s_nop 0
	v_pk_mul_f32 v[90:91], v[90:91], v[96:97]
	s_nop 0
	v_pk_mul_f32 v[90:91], v[90:91], v[104:105]
	s_nop 0
	v_cvt_pk_bf16_f32 v90, v90, v91
	v_mul_f32_e32 v91, 0xbfb8aa3b, v92
	v_exp_f32_e32 v91, v91
	s_nop 0
	v_add_f32_e32 v91, 1.0, v91
	v_rcp_f32_e32 v96, v91
	v_mul_f32_e32 v91, 0xbfb8aa3b, v93
	v_exp_f32_e32 v91, v91
	s_nop 0
	v_add_f32_e32 v91, 1.0, v91
	v_rcp_f32_e32 v97, v91
	s_nop 0
	v_pk_mul_f32 v[92:93], v[92:93], v[96:97]
	s_nop 0
	v_pk_mul_f32 v[92:93], v[92:93], v[106:107]
	s_nop 0
	v_cvt_pk_bf16_f32 v91, v92, v93
	v_lshlrev_b64 v[92:93], 11, v[98:99]
	v_add_u32_e32 v98, 0x2001, v120
	v_lshl_add_u64 v[92:93], v[88:89], 0, v[92:93]
	v_ashrrev_i32_e32 v99, 31, v98
	global_store_dwordx2 v[92:93], v[94:95], off
	global_store_dwordx2 v[92:93], v[90:91], off offset:512
	v_lshlrev_b64 v[90:91], 10, v[98:99]
	v_lshl_add_u64 v[90:91], v[86:87], 0, v[90:91]
	ds_read_b128 v[94:97], v223
	s_waitcnt lgkmcnt(0)
	v_mov_b32_e32 v114, v94
	v_mov_b32_e32 v115, v96
	v_pk_mul_f32 v[114:115], v[114:115], v[114:115]
	v_pk_mul_f32 v[116:117], v[94:95], v[94:95]
	v_mov_b32_e32 v118, v114
	v_mov_b32_e32 v119, v94
	v_mov_b32_e32 v116, v117
	v_mov_b32_e32 v117, v95
	v_pk_mul_f32 v[112:113], v[96:97], v[96:97]
	v_pk_add_f32 v[116:117], v[118:119], v[116:117]
	v_pk_mov_b32 v[114:115], v[114:115], v[96:97] op_sel:[1,0]
	v_mov_b32_e32 v112, v113
	v_pk_add_f32 v[114:115], v[116:117], v[114:115]
	v_mov_b32_e32 v113, v97
	v_pk_add_f32 v[112:113], v[114:115], v[112:113]
	v_lshlrev_b32_e32 v100, 16, v132
	v_and_b32_e32 v101, 0xffff0000, v132
	v_lshlrev_b32_e32 v102, 16, v133
	v_and_b32_e32 v103, 0xffff0000, v133
	v_lshlrev_b32_e32 v104, 16, v134
	v_and_b32_e32 v105, 0xffff0000, v134
	v_lshlrev_b32_e32 v106, 16, v135
	v_and_b32_e32 v107, 0xffff0000, v135
	ds_read_b128 v[90:93], v223 offset:1024
	s_waitcnt lgkmcnt(0)
	v_pk_mul_f32 v[110:111], v[90:91], v[90:91]
	s_nop 0
	v_mov_b32_e32 v114, v110
	v_mov_b32_e32 v115, v90
	v_pk_mul_f32 v[108:109], v[92:93], v[92:93]
	v_pk_add_f32 v[112:113], v[112:113], v[114:115]
	v_mov_b32_e32 v110, v111
	v_mov_b32_e32 v111, v91
	v_pk_add_f32 v[110:111], v[112:113], v[110:111]
	v_mov_b32_e32 v112, v108
	v_mov_b32_e32 v113, v92
	v_pk_add_f32 v[110:111], v[110:111], v[112:113]
	v_mov_b32_e32 v108, v109
	v_mov_b32_e32 v109, v93
	v_pk_add_f32 v[108:109], v[110:111], v[108:109]
	ds_bpermute_b32 v111, v217, v109
	ds_bpermute_b32 v110, v217, v108
	s_waitcnt lgkmcnt(0)
	v_pk_add_f32 v[108:109], v[108:109], v[110:111]
	ds_bpermute_b32 v111, v218, v109
	ds_bpermute_b32 v110, v218, v108
	s_waitcnt lgkmcnt(0)
	v_pk_add_f32 v[108:109], v[108:109], v[110:111]
	ds_bpermute_b32 v111, v219, v109
	ds_bpermute_b32 v110, v219, v108
	s_waitcnt lgkmcnt(0)
	v_pk_add_f32 v[108:109], v[108:109], v[110:111]
	ds_bpermute_b32 v111, v220, v109
	ds_bpermute_b32 v110, v220, v108
	s_waitcnt lgkmcnt(0)
	v_pk_add_f32 v[108:109], v[108:109], v[110:111]
	ds_bpermute_b32 v111, v221, v109
	ds_bpermute_b32 v110, v221, v108
	s_waitcnt lgkmcnt(0)
	v_pk_add_f32 v[108:109], v[108:109], v[110:111]
	ds_bpermute_b32 v111, v222, v109
	ds_bpermute_b32 v110, v222, v108
	s_waitcnt lgkmcnt(0)
	v_pk_add_f32 v[108:109], v[108:109], v[110:111]
	s_nop 0
	v_pk_mul_f32 v[108:109], v[108:109], s[6:7] op_sel_hi:[1,0]
	s_nop 0
	v_fma_f32 v110, -v109, v109, v108
	v_max_f32_e32 v110, 0, v110
	v_add_f32_e32 v110, 0x358637bd, v110
	v_cmp_gt_f32_e32 vcc, s22, v110
	v_mul_f32_e32 v111, 0x4b800000, v110
	v_pk_add_f32 v[94:95], v[94:95], v[108:109] op_sel:[0,1] neg_lo:[0,1] neg_hi:[0,1]
	v_cndmask_b32_e32 v110, v110, v111, vcc
	v_rsq_f32_e32 v110, v110
	v_pk_add_f32 v[96:97], v[96:97], v[108:109] op_sel:[0,1] neg_lo:[0,1] neg_hi:[0,1]
	v_pk_add_f32 v[90:91], v[90:91], v[108:109] op_sel:[0,1] neg_lo:[0,1] neg_hi:[0,1]
	v_pk_add_f32 v[92:93], v[92:93], v[108:109] op_sel:[0,1] neg_lo:[0,1] neg_hi:[0,1]
	v_mul_f32_e32 v111, 0x45800000, v110
	v_cndmask_b32_e32 v110, v110, v111, vcc
	v_pk_mul_f32 v[94:95], v[94:95], v[110:111] op_sel_hi:[1,0]
	s_nop 0
	v_pk_fma_f32 v[94:95], v[10:11], v[94:95], v[14:15]
	s_nop 0
	v_mul_f32_e32 v111, 0xbfb8aa3b, v94
	v_exp_f32_e32 v111, v111
	s_nop 0
	v_add_f32_e32 v111, 1.0, v111
	v_rcp_f32_e32 v112, v111
	v_mul_f32_e32 v111, 0xbfb8aa3b, v95
	v_exp_f32_e32 v111, v111
	s_nop 0
	v_add_f32_e32 v111, 1.0, v111
	v_rcp_f32_e32 v113, v111
	v_pk_mul_f32 v[96:97], v[96:97], v[110:111] op_sel_hi:[1,0]
	v_pk_mul_f32 v[90:91], v[90:91], v[110:111] op_sel_hi:[1,0]
	v_pk_fma_f32 v[96:97], v[12:13], v[96:97], v[16:17]
	v_pk_mul_f32 v[94:95], v[94:95], v[112:113]
	v_pk_fma_f32 v[90:91], v[2:3], v[90:91], v[6:7]
	v_pk_mul_f32 v[94:95], v[94:95], v[100:101]
	v_pk_mul_f32 v[92:93], v[92:93], v[110:111] op_sel_hi:[1,0]
	v_cvt_pk_bf16_f32 v94, v94, v95
	v_mul_f32_e32 v95, 0xbfb8aa3b, v96
	v_exp_f32_e32 v95, v95
	v_pk_fma_f32 v[92:93], v[4:5], v[92:93], v[8:9]
	v_add_f32_e32 v95, 1.0, v95
	v_rcp_f32_e32 v100, v95
	v_mul_f32_e32 v95, 0xbfb8aa3b, v97
	v_exp_f32_e32 v95, v95
	s_nop 0
	v_add_f32_e32 v95, 1.0, v95
	v_rcp_f32_e32 v101, v95
	s_nop 0
	v_pk_mul_f32 v[96:97], v[96:97], v[100:101]
	s_nop 0
	v_pk_mul_f32 v[96:97], v[96:97], v[102:103]
	s_nop 0
	v_cvt_pk_bf16_f32 v95, v96, v97
	v_mul_f32_e32 v96, 0xbfb8aa3b, v90
	v_mul_f32_e32 v97, 0xbfb8aa3b, v91
	v_exp_f32_e32 v96, v96
	v_exp_f32_e32 v97, v97
	v_add_f32_e32 v96, 1.0, v96
	v_add_f32_e32 v97, 1.0, v97
	v_rcp_f32_e32 v96, v96
	v_rcp_f32_e32 v97, v97
	s_nop 0
	v_pk_mul_f32 v[90:91], v[90:91], v[96:97]
	s_nop 0
	v_pk_mul_f32 v[90:91], v[90:91], v[104:105]
	s_nop 0
	v_cvt_pk_bf16_f32 v90, v90, v91
	v_mul_f32_e32 v91, 0xbfb8aa3b, v92
	v_exp_f32_e32 v91, v91
	s_nop 0
	v_add_f32_e32 v91, 1.0, v91
	v_rcp_f32_e32 v96, v91
	v_mul_f32_e32 v91, 0xbfb8aa3b, v93
	v_exp_f32_e32 v91, v91
	s_nop 0
	v_add_f32_e32 v91, 1.0, v91
	v_rcp_f32_e32 v97, v91
	s_nop 0
	v_pk_mul_f32 v[92:93], v[92:93], v[96:97]
	s_nop 0
	v_pk_mul_f32 v[92:93], v[92:93], v[106:107]
	s_nop 0
	v_cvt_pk_bf16_f32 v91, v92, v93
	v_lshlrev_b64 v[92:93], 11, v[98:99]
	v_add_u32_e32 v98, 0x2002, v120
	v_lshl_add_u64 v[92:93], v[88:89], 0, v[92:93]
	v_ashrrev_i32_e32 v99, 31, v98
	global_store_dwordx2 v[92:93], v[94:95], off
	global_store_dwordx2 v[92:93], v[90:91], off offset:512
	v_lshlrev_b64 v[90:91], 10, v[98:99]
	v_lshl_add_u64 v[90:91], v[86:87], 0, v[90:91]
	ds_read_b128 v[94:97], v224
	s_waitcnt lgkmcnt(0)
	v_mov_b32_e32 v114, v94
	v_mov_b32_e32 v115, v96
	v_pk_mul_f32 v[114:115], v[114:115], v[114:115]
	v_pk_mul_f32 v[116:117], v[94:95], v[94:95]
	v_mov_b32_e32 v118, v114
	v_mov_b32_e32 v119, v94
	v_mov_b32_e32 v116, v117
	v_mov_b32_e32 v117, v95
	v_pk_mul_f32 v[112:113], v[96:97], v[96:97]
	v_pk_add_f32 v[116:117], v[118:119], v[116:117]
	v_pk_mov_b32 v[114:115], v[114:115], v[96:97] op_sel:[1,0]
	v_mov_b32_e32 v112, v113
	v_pk_add_f32 v[114:115], v[116:117], v[114:115]
	v_mov_b32_e32 v113, v97
	v_pk_add_f32 v[112:113], v[114:115], v[112:113]
	v_lshlrev_b32_e32 v100, 16, v136
	v_and_b32_e32 v101, 0xffff0000, v136
	v_lshlrev_b32_e32 v102, 16, v137
	v_and_b32_e32 v103, 0xffff0000, v137
	v_lshlrev_b32_e32 v104, 16, v138
	v_and_b32_e32 v105, 0xffff0000, v138
	v_lshlrev_b32_e32 v106, 16, v139
	v_and_b32_e32 v107, 0xffff0000, v139
	ds_read_b128 v[90:93], v224 offset:1024
	s_waitcnt lgkmcnt(0)
	v_pk_mul_f32 v[110:111], v[90:91], v[90:91]
	s_nop 0
	v_mov_b32_e32 v114, v110
	v_mov_b32_e32 v115, v90
	v_pk_mul_f32 v[108:109], v[92:93], v[92:93]
	v_pk_add_f32 v[112:113], v[112:113], v[114:115]
	v_mov_b32_e32 v110, v111
	v_mov_b32_e32 v111, v91
	v_pk_add_f32 v[110:111], v[112:113], v[110:111]
	v_mov_b32_e32 v112, v108
	v_mov_b32_e32 v113, v92
	v_pk_add_f32 v[110:111], v[110:111], v[112:113]
	v_mov_b32_e32 v108, v109
	v_mov_b32_e32 v109, v93
	v_pk_add_f32 v[108:109], v[110:111], v[108:109]
	ds_bpermute_b32 v111, v217, v109
	ds_bpermute_b32 v110, v217, v108
	s_waitcnt lgkmcnt(0)
	v_pk_add_f32 v[108:109], v[108:109], v[110:111]
	ds_bpermute_b32 v111, v218, v109
	ds_bpermute_b32 v110, v218, v108
	s_waitcnt lgkmcnt(0)
	v_pk_add_f32 v[108:109], v[108:109], v[110:111]
	ds_bpermute_b32 v111, v219, v109
	ds_bpermute_b32 v110, v219, v108
	s_waitcnt lgkmcnt(0)
	v_pk_add_f32 v[108:109], v[108:109], v[110:111]
	ds_bpermute_b32 v111, v220, v109
	ds_bpermute_b32 v110, v220, v108
	s_waitcnt lgkmcnt(0)
	v_pk_add_f32 v[108:109], v[108:109], v[110:111]
	ds_bpermute_b32 v111, v221, v109
	ds_bpermute_b32 v110, v221, v108
	s_waitcnt lgkmcnt(0)
	v_pk_add_f32 v[108:109], v[108:109], v[110:111]
	ds_bpermute_b32 v111, v222, v109
	ds_bpermute_b32 v110, v222, v108
	s_waitcnt lgkmcnt(0)
	v_pk_add_f32 v[108:109], v[108:109], v[110:111]
	s_nop 0
	v_pk_mul_f32 v[108:109], v[108:109], s[6:7] op_sel_hi:[1,0]
	s_nop 0
	v_fma_f32 v110, -v109, v109, v108
	v_max_f32_e32 v110, 0, v110
	v_add_f32_e32 v110, 0x358637bd, v110
	v_cmp_gt_f32_e32 vcc, s22, v110
	v_mul_f32_e32 v111, 0x4b800000, v110
	v_pk_add_f32 v[94:95], v[94:95], v[108:109] op_sel:[0,1] neg_lo:[0,1] neg_hi:[0,1]
	v_cndmask_b32_e32 v110, v110, v111, vcc
	v_rsq_f32_e32 v110, v110
	v_pk_add_f32 v[96:97], v[96:97], v[108:109] op_sel:[0,1] neg_lo:[0,1] neg_hi:[0,1]
	v_pk_add_f32 v[90:91], v[90:91], v[108:109] op_sel:[0,1] neg_lo:[0,1] neg_hi:[0,1]
	v_pk_add_f32 v[92:93], v[92:93], v[108:109] op_sel:[0,1] neg_lo:[0,1] neg_hi:[0,1]
	v_mul_f32_e32 v111, 0x45800000, v110
	v_cndmask_b32_e32 v110, v110, v111, vcc
	v_pk_mul_f32 v[94:95], v[94:95], v[110:111] op_sel_hi:[1,0]
	s_nop 0
	v_pk_fma_f32 v[94:95], v[10:11], v[94:95], v[14:15]
	s_nop 0
	v_mul_f32_e32 v111, 0xbfb8aa3b, v94
	v_exp_f32_e32 v111, v111
	s_nop 0
	v_add_f32_e32 v111, 1.0, v111
	v_rcp_f32_e32 v112, v111
	v_mul_f32_e32 v111, 0xbfb8aa3b, v95
	v_exp_f32_e32 v111, v111
	s_nop 0
	v_add_f32_e32 v111, 1.0, v111
	v_rcp_f32_e32 v113, v111
	v_pk_mul_f32 v[96:97], v[96:97], v[110:111] op_sel_hi:[1,0]
	v_pk_mul_f32 v[90:91], v[90:91], v[110:111] op_sel_hi:[1,0]
	v_pk_fma_f32 v[96:97], v[12:13], v[96:97], v[16:17]
	v_pk_mul_f32 v[94:95], v[94:95], v[112:113]
	v_pk_fma_f32 v[90:91], v[2:3], v[90:91], v[6:7]
	v_pk_mul_f32 v[94:95], v[94:95], v[100:101]
	v_pk_mul_f32 v[92:93], v[92:93], v[110:111] op_sel_hi:[1,0]
	v_cvt_pk_bf16_f32 v94, v94, v95
	v_mul_f32_e32 v95, 0xbfb8aa3b, v96
	v_exp_f32_e32 v95, v95
	v_pk_fma_f32 v[92:93], v[4:5], v[92:93], v[8:9]
	v_add_f32_e32 v95, 1.0, v95
	v_rcp_f32_e32 v100, v95
	v_mul_f32_e32 v95, 0xbfb8aa3b, v97
	v_exp_f32_e32 v95, v95
	s_nop 0
	v_add_f32_e32 v95, 1.0, v95
	v_rcp_f32_e32 v101, v95
	s_nop 0
	v_pk_mul_f32 v[96:97], v[96:97], v[100:101]
	s_nop 0
	v_pk_mul_f32 v[96:97], v[96:97], v[102:103]
	s_nop 0
	v_cvt_pk_bf16_f32 v95, v96, v97
	v_mul_f32_e32 v96, 0xbfb8aa3b, v90
	v_mul_f32_e32 v97, 0xbfb8aa3b, v91
	v_exp_f32_e32 v96, v96
	v_exp_f32_e32 v97, v97
	v_add_f32_e32 v96, 1.0, v96
	v_add_f32_e32 v97, 1.0, v97
	v_rcp_f32_e32 v96, v96
	v_rcp_f32_e32 v97, v97
	s_nop 0
	v_pk_mul_f32 v[90:91], v[90:91], v[96:97]
	s_nop 0
	v_pk_mul_f32 v[90:91], v[90:91], v[104:105]
	s_nop 0
	v_cvt_pk_bf16_f32 v90, v90, v91
	v_mul_f32_e32 v91, 0xbfb8aa3b, v92
	v_exp_f32_e32 v91, v91
	s_nop 0
	v_add_f32_e32 v91, 1.0, v91
	v_rcp_f32_e32 v96, v91
	v_mul_f32_e32 v91, 0xbfb8aa3b, v93
	v_exp_f32_e32 v91, v91
	s_nop 0
	v_add_f32_e32 v91, 1.0, v91
	v_rcp_f32_e32 v97, v91
	s_nop 0
	v_pk_mul_f32 v[92:93], v[92:93], v[96:97]
	s_nop 0
	v_pk_mul_f32 v[92:93], v[92:93], v[106:107]
	s_nop 0
	v_cvt_pk_bf16_f32 v91, v92, v93
	v_lshlrev_b64 v[92:93], 11, v[98:99]
	v_add_u32_e32 v98, 0x2003, v120
	v_lshl_add_u64 v[92:93], v[88:89], 0, v[92:93]
	v_ashrrev_i32_e32 v99, 31, v98
	global_store_dwordx2 v[92:93], v[94:95], off
	global_store_dwordx2 v[92:93], v[90:91], off offset:512
	v_lshlrev_b64 v[90:91], 10, v[98:99]
	v_lshl_add_u64 v[90:91], v[86:87], 0, v[90:91]
	ds_read_b128 v[94:97], v225
	s_waitcnt lgkmcnt(0)
	v_mov_b32_e32 v114, v94
	v_mov_b32_e32 v115, v96
	v_pk_mul_f32 v[114:115], v[114:115], v[114:115]
	v_pk_mul_f32 v[116:117], v[94:95], v[94:95]
	v_mov_b32_e32 v118, v114
	v_mov_b32_e32 v119, v94
	v_mov_b32_e32 v116, v117
	v_mov_b32_e32 v117, v95
	v_pk_mul_f32 v[112:113], v[96:97], v[96:97]
	v_pk_add_f32 v[116:117], v[118:119], v[116:117]
	v_pk_mov_b32 v[114:115], v[114:115], v[96:97] op_sel:[1,0]
	v_mov_b32_e32 v112, v113
	v_pk_add_f32 v[114:115], v[116:117], v[114:115]
	v_mov_b32_e32 v113, v97
	v_pk_add_f32 v[112:113], v[114:115], v[112:113]
	v_lshlrev_b32_e32 v100, 16, v140
	v_and_b32_e32 v101, 0xffff0000, v140
	v_lshlrev_b32_e32 v102, 16, v141
	v_and_b32_e32 v103, 0xffff0000, v141
	v_lshlrev_b32_e32 v104, 16, v142
	v_and_b32_e32 v105, 0xffff0000, v142
	v_lshlrev_b32_e32 v106, 16, v143
	v_and_b32_e32 v107, 0xffff0000, v143
	ds_read_b128 v[90:93], v225 offset:1024
	s_waitcnt lgkmcnt(0)
	v_pk_mul_f32 v[110:111], v[90:91], v[90:91]
	s_nop 0
	v_mov_b32_e32 v114, v110
	v_mov_b32_e32 v115, v90
	v_pk_mul_f32 v[108:109], v[92:93], v[92:93]
	v_pk_add_f32 v[112:113], v[112:113], v[114:115]
	v_mov_b32_e32 v110, v111
	v_mov_b32_e32 v111, v91
	v_pk_add_f32 v[110:111], v[112:113], v[110:111]
	v_mov_b32_e32 v112, v108
	v_mov_b32_e32 v113, v92
	v_pk_add_f32 v[110:111], v[110:111], v[112:113]
	v_mov_b32_e32 v108, v109
	v_mov_b32_e32 v109, v93
	v_pk_add_f32 v[108:109], v[110:111], v[108:109]
	ds_bpermute_b32 v111, v217, v109
	ds_bpermute_b32 v110, v217, v108
	s_waitcnt lgkmcnt(0)
	v_pk_add_f32 v[108:109], v[108:109], v[110:111]
	ds_bpermute_b32 v111, v218, v109
	ds_bpermute_b32 v110, v218, v108
	s_waitcnt lgkmcnt(0)
	v_pk_add_f32 v[108:109], v[108:109], v[110:111]
	ds_bpermute_b32 v111, v219, v109
	ds_bpermute_b32 v110, v219, v108
	s_waitcnt lgkmcnt(0)
	v_pk_add_f32 v[108:109], v[108:109], v[110:111]
	ds_bpermute_b32 v111, v220, v109
	ds_bpermute_b32 v110, v220, v108
	s_waitcnt lgkmcnt(0)
	v_pk_add_f32 v[108:109], v[108:109], v[110:111]
	ds_bpermute_b32 v111, v221, v109
	ds_bpermute_b32 v110, v221, v108
	s_waitcnt lgkmcnt(0)
	v_pk_add_f32 v[108:109], v[108:109], v[110:111]
	ds_bpermute_b32 v111, v222, v109
	ds_bpermute_b32 v110, v222, v108
	s_waitcnt lgkmcnt(0)
	v_pk_add_f32 v[108:109], v[108:109], v[110:111]
	s_nop 0
	v_pk_mul_f32 v[108:109], v[108:109], s[6:7] op_sel_hi:[1,0]
	s_nop 0
	v_fma_f32 v110, -v109, v109, v108
	v_max_f32_e32 v110, 0, v110
	v_add_f32_e32 v110, 0x358637bd, v110
	v_cmp_gt_f32_e32 vcc, s22, v110
	v_mul_f32_e32 v111, 0x4b800000, v110
	v_pk_add_f32 v[94:95], v[94:95], v[108:109] op_sel:[0,1] neg_lo:[0,1] neg_hi:[0,1]
	v_cndmask_b32_e32 v110, v110, v111, vcc
	v_rsq_f32_e32 v110, v110
	s_nop 0
	v_mul_f32_e32 v111, 0x45800000, v110
	v_cndmask_b32_e32 v110, v110, v111, vcc
	v_pk_mul_f32 v[94:95], v[94:95], v[110:111] op_sel_hi:[1,0]
	v_cmp_lt_i32_e32 vcc, s23, v1
	v_pk_fma_f32 v[10:11], v[10:11], v[94:95], v[14:15]
	s_or_b64 s[4:5], vcc, s[4:5]
	v_mul_f32_e32 v14, 0xbfb8aa3b, v10
	v_mul_f32_e32 v15, 0xbfb8aa3b, v11
	v_exp_f32_e32 v14, v14
	v_exp_f32_e32 v15, v15
	v_add_f32_e32 v14, 1.0, v14
	v_add_f32_e32 v15, 1.0, v15
	v_rcp_f32_e32 v14, v14
	v_rcp_f32_e32 v15, v15
	s_nop 0
	v_pk_mul_f32 v[10:11], v[10:11], v[14:15]
	v_pk_add_f32 v[14:15], v[96:97], v[108:109] op_sel:[0,1] neg_lo:[0,1] neg_hi:[0,1]
	v_pk_mul_f32 v[10:11], v[10:11], v[100:101]
	v_pk_mul_f32 v[14:15], v[14:15], v[110:111] op_sel_hi:[1,0]
	v_cvt_pk_bf16_f32 v10, v10, v11
	v_pk_fma_f32 v[12:13], v[12:13], v[14:15], v[16:17]
	s_nop 0
	v_mul_f32_e32 v11, 0xbfb8aa3b, v12
	v_exp_f32_e32 v11, v11
	s_nop 0
	v_add_f32_e32 v11, 1.0, v11
	v_rcp_f32_e32 v14, v11
	v_mul_f32_e32 v11, 0xbfb8aa3b, v13
	v_exp_f32_e32 v11, v11
	s_nop 0
	v_add_f32_e32 v11, 1.0, v11
	v_rcp_f32_e32 v15, v11
	s_nop 0
	v_pk_mul_f32 v[12:13], v[12:13], v[14:15]
	s_nop 0
	v_pk_mul_f32 v[12:13], v[12:13], v[102:103]
	s_nop 0
	v_cvt_pk_bf16_f32 v11, v12, v13
	v_pk_add_f32 v[12:13], v[90:91], v[108:109] op_sel:[0,1] neg_lo:[0,1] neg_hi:[0,1]
	s_nop 0
	v_pk_mul_f32 v[12:13], v[12:13], v[110:111] op_sel_hi:[1,0]
	s_nop 0
	v_pk_fma_f32 v[2:3], v[2:3], v[12:13], v[6:7]
	s_nop 0
	v_mul_f32_e32 v6, 0xbfb8aa3b, v2
	v_mul_f32_e32 v7, 0xbfb8aa3b, v3
	v_exp_f32_e32 v6, v6
	v_exp_f32_e32 v7, v7
	v_add_f32_e32 v6, 1.0, v6
	v_add_f32_e32 v7, 1.0, v7
	v_rcp_f32_e32 v6, v6
	v_rcp_f32_e32 v7, v7
	s_nop 0
	v_pk_mul_f32 v[2:3], v[2:3], v[6:7]
	v_pk_add_f32 v[6:7], v[92:93], v[108:109] op_sel:[0,1] neg_lo:[0,1] neg_hi:[0,1]
	v_pk_mul_f32 v[2:3], v[2:3], v[104:105]
	v_pk_mul_f32 v[6:7], v[6:7], v[110:111] op_sel_hi:[1,0]
	v_cvt_pk_bf16_f32 v2, v2, v3
	v_pk_fma_f32 v[4:5], v[4:5], v[6:7], v[8:9]
	s_nop 0
	v_mul_f32_e32 v3, 0xbfb8aa3b, v4
	v_exp_f32_e32 v3, v3
	s_nop 0
	v_add_f32_e32 v3, 1.0, v3
	v_rcp_f32_e32 v6, v3
	v_mul_f32_e32 v3, 0xbfb8aa3b, v5
	v_exp_f32_e32 v3, v3
	s_nop 0
	v_add_f32_e32 v3, 1.0, v3
	v_rcp_f32_e32 v7, v3
	s_nop 0
	v_pk_mul_f32 v[4:5], v[4:5], v[6:7]
	s_nop 0
	v_pk_mul_f32 v[4:5], v[4:5], v[106:107]
	s_nop 0
	v_cvt_pk_bf16_f32 v3, v4, v5
	v_lshlrev_b64 v[4:5], 11, v[98:99]
	v_lshl_add_u64 v[4:5], v[88:89], 0, v[4:5]
	global_store_dwordx2 v[4:5], v[10:11], off
	global_store_dwordx2 v[4:5], v[2:3], off offset:512
	s_andn2_b64 exec, exec, s[4:5]
	s_cbranch_execnz .LBB0_555
